# FFN-F2 conv epilogue: row-neighbour shuffles by DPP row rotate instead of ds_bpermute through LDS (same code size)
# speedup vs baseline: 1.0124x; 1.0019x over previous
.LBB0_1060:
	s_lshl_b32 s0, s3, 8
	s_add_i32 s0, s0, s60
	s_cmpk_lt_i32 s0, 0x2000
	s_movk_i32 s20, 0xfff
	v_lshl_or_b32 v192, s2, 8, v223
	s_cselect_b32 s14, s20, 0x7ff
	s_or_b32 s2, s0, 63
	s_and_b32 s1, s14, s0
	s_and_b32 s15, s14, s2
	v_or_b32_e32 v226, s0, v221
	v_mov_b64_e32 v[208:209], s[10:11]
	s_movk_i32 s26, 0x2c00
	v_ashrrev_i32_e32 v193, 31, v192
	v_mad_i64_i32 v[152:153], s[2:3], v226, s26, v[208:209]
	s_cmp_eq_u32 s1, 0
	s_mul_i32 s1, s0, 0x2c00
	v_lshlrev_b64 v[204:205], 1, v[192:193]
	s_cselect_b64 s[62:63], -1, 0
	s_mul_hi_i32 s3, s0, 0x2c00
	s_add_u32 s2, s10, s1
	v_lshl_add_u64 v[194:195], v[152:153], 0, v[204:205]
	s_mov_b32 s21, 0x2c000
	s_addc_u32 s3, s11, s3
	v_add_co_u32_e32 v198, vcc, s21, v194
	s_and_b64 s[12:13], s[62:63], exec
	s_nop 0
	v_addc_co_u32_e32 v199, vcc, 0, v195, vcc
	s_mov_b32 s22, 0x58000
	s_cselect_b32 s12, 0, 0xffffd400
	s_cselect_b32 s13, 0, -1
	s_cmp_eq_u32 s15, s14
	v_add_co_u32_e32 v200, vcc, s22, v194
	s_cselect_b64 s[50:51], -1, 0
	v_lshlrev_b64 v[88:89], 2, v[192:193]
	v_addc_co_u32_e32 v201, vcc, 0, v195, vcc
	s_mov_b32 s23, 0x84000
	v_lshl_add_u64 v[202:203], s[2:3], 0, v[204:205]
	s_and_b64 s[2:3], s[50:51], exec
	v_lshl_add_u64 v[190:191], s[18:19], 0, v[88:89]
	v_lshl_add_u64 v[90:91], s[46:47], 0, v[88:89]
	v_lshl_add_u64 v[96:97], s[48:49], 0, v[88:89]
	v_add_co_u32_e32 v206, vcc, s23, v194
	s_cselect_b32 s72, 0, 0xb0000
	v_lshl_add_u64 v[188:189], s[30:31], 0, v[88:89]
	global_load_dwordx4 v[100:103], v[190:191], off offset:16
	global_load_dwordx4 v[120:123], v[190:191], off
	global_load_dwordx4 v[92:95], v[90:91], off offset:16
	global_load_dwordx4 v[112:115], v[90:91], off
	s_nop 0
	global_load_dwordx4 v[88:91], v[96:97], off offset:16
	global_load_dwordx4 v[108:111], v[96:97], off
	s_nop 0
	global_load_dwordx4 v[96:99], v[188:189], off offset:16
	global_load_dwordx4 v[116:119], v[188:189], off
	global_load_dwordx4 v[172:175], v[194:195], off
	v_addc_co_u32_e32 v207, vcc, 0, v195, vcc
	v_lshl_add_u64 v[196:197], v[202:203], 0, s[12:13]
	v_lshl_add_u64 v[202:203], v[202:203], 0, s[72:73]
	global_load_dwordx4 v[168:171], v[198:199], off
	global_load_dwordx4 v[164:167], v[200:201], off
	global_load_dwordx4 v[152:155], v[206:207], off
	global_load_dwordx4 v[232:235], v[202:203], off
	global_load_dwordx4 v[228:231], v[196:197], off
	v_or_b32_e32 v193, v211, v219
	v_lshlrev_b32_e32 v193, 2, v193
	v_or_b32_e32 v225, v219, v212
	v_lshlrev_b32_e32 v225, 2, v225
	s_add_i32 s12, s0, 0x80
	s_cmpk_lt_i32 s12, 0x2000
	s_cselect_b32 s13, s20, 0x7ff
	s_addk_i32 s0, 0xbf
	s_and_b32 s14, s13, s12
	s_and_b32 s15, s13, s0
	s_cmp_eq_u32 s14, 0
	s_waitcnt vmcnt(0)
	v_mov_b32_dpp v239, v172 row_ror:1 row_mask:0xf bank_mask:0xf
	v_mov_b32_dpp v240, v173 row_ror:1 row_mask:0xf bank_mask:0xf
	v_mov_b32_dpp v241, v174 row_ror:1 row_mask:0xf bank_mask:0xf
	v_mov_b32_dpp v242, v175 row_ror:1 row_mask:0xf bank_mask:0xf
	v_mov_b32_dpp v243, v168 row_ror:15 row_mask:0xf bank_mask:0xf
	v_mov_b32_dpp v244, v169 row_ror:15 row_mask:0xf bank_mask:0xf
	v_mov_b32_dpp v245, v170 row_ror:15 row_mask:0xf bank_mask:0xf
	v_cndmask_b32_e64 v227, v235, 0, s[50:51]
	v_cndmask_b32_e64 v236, v230, 0, s[62:63]
	v_cndmask_b32_e64 v237, v229, 0, s[62:63]
	v_cndmask_b32_e64 v229, v233, 0, s[50:51]
	v_cndmask_b32_e64 v230, v232, 0, s[50:51]
	v_mov_b32_dpp v232, v172 row_ror:15 row_mask:0xf bank_mask:0xf
	v_mov_b32_dpp v233, v173 row_ror:15 row_mask:0xf bank_mask:0xf
	v_cndmask_b32_e64 v238, v228, 0, s[62:63]
	v_cndmask_b32_e64 v228, v234, 0, s[50:51]
	v_mov_b32_dpp v234, v174 row_ror:15 row_mask:0xf bank_mask:0xf
	v_mov_b32_dpp v235, v175 row_ror:15 row_mask:0xf bank_mask:0xf
	v_mov_b32_dpp v246, v171 row_ror:15 row_mask:0xf bank_mask:0xf
	s_waitcnt lgkmcnt(0)
	v_cndmask_b32_e64 v238, v239, v238, s[4:5]
	s_waitcnt lgkmcnt(0)
	v_cndmask_b32_e64 v247, v232, v243, s[6:7]
	s_waitcnt lgkmcnt(0)
	v_cndmask_b32_e64 v249, v233, v244, s[6:7]
	v_lshlrev_b32_e32 v232, 16, v238
	v_and_b32_e32 v233, 0xffff0000, v238
	v_cndmask_b32_e64 v248, v240, v237, s[4:5]
	v_cndmask_b32_e64 v250, v241, v236, s[4:5]
	v_pk_mul_f32 v[232:233], v[120:121], v[232:233]
	v_lshlrev_b32_e32 v236, 16, v172
	v_and_b32_e32 v237, 0xffff0000, v172
	s_waitcnt lgkmcnt(0)
	v_cndmask_b32_e64 v251, v234, v245, s[6:7]
	s_waitcnt lgkmcnt(0)
	v_cndmask_b32_e64 v252, v235, v246, s[6:7]
	v_lshlrev_b32_e32 v234, 16, v247
	v_and_b32_e32 v235, 0xffff0000, v247
	v_pk_fma_f32 v[232:233], v[112:113], v[236:237], v[232:233]
	v_cndmask_b32_e64 v231, v231, 0, s[62:63]
	v_pk_fma_f32 v[232:233], v[108:109], v[234:235], v[232:233]
	v_cndmask_b32_e64 v231, v242, v231, s[4:5]
	v_pk_add_f32 v[232:233], v[116:117], v[232:233]
	v_mov_b32_dpp v236, v166 row_ror:15 row_mask:0xf bank_mask:0xf
	v_mul_f32_e32 v172, 0xbfb8aa3b, v232
	v_exp_f32_e32 v172, v172
	v_mov_b32_dpp v237, v167 row_ror:15 row_mask:0xf bank_mask:0xf
	v_add_f32_e32 v172, 1.0, v172
	v_rcp_f32_e32 v234, v172
	v_mul_f32_e32 v172, 0xbfb8aa3b, v233
	v_exp_f32_e32 v172, v172
	s_nop 0
	v_add_f32_e32 v172, 1.0, v172
	v_rcp_f32_e32 v235, v172
	v_lshlrev_b32_e32 v172, 16, v173
	v_and_b32_e32 v173, 0xffff0000, v173
	v_pk_mul_f32 v[232:233], v[232:233], v[234:235]
	s_nop 0
	v_pk_mul_f32 v[160:161], v[160:161], v[232:233]
	v_lshlrev_b32_e32 v232, 16, v248
	v_and_b32_e32 v233, 0xffff0000, v248
	v_pk_mul_f32 v[232:233], v[122:123], v[232:233]
	v_lshlrev_b32_e32 v234, 16, v249
	v_and_b32_e32 v235, 0xffff0000, v249
	v_pk_fma_f32 v[172:173], v[114:115], v[172:173], v[232:233]
	s_nop 0
	v_pk_fma_f32 v[172:173], v[110:111], v[234:235], v[172:173]
	v_lshlrev_b32_e32 v234, 16, v174
	v_pk_add_f32 v[172:173], v[118:119], v[172:173]
	v_and_b32_e32 v235, 0xffff0000, v174
	v_mul_f32_e32 v232, 0xbfb8aa3b, v172
	v_mul_f32_e32 v233, 0xbfb8aa3b, v173
	v_exp_f32_e32 v232, v232
	v_exp_f32_e32 v233, v233
	v_add_f32_e32 v232, 1.0, v232
	v_add_f32_e32 v233, 1.0, v233
	v_rcp_f32_e32 v232, v232
	v_rcp_f32_e32 v233, v233
	s_nop 0
	v_pk_mul_f32 v[172:173], v[172:173], v[232:233]
	s_nop 0
	v_pk_mul_f32 v[162:163], v[162:163], v[172:173]
	v_lshlrev_b32_e32 v172, 16, v250
	v_and_b32_e32 v173, 0xffff0000, v250
	v_pk_mul_f32 v[172:173], v[100:101], v[172:173]
	v_lshlrev_b32_e32 v232, 16, v251
	v_and_b32_e32 v233, 0xffff0000, v251
	v_pk_fma_f32 v[172:173], v[92:93], v[234:235], v[172:173]
	v_mov_b32_dpp v234, v164 row_ror:15 row_mask:0xf bank_mask:0xf
	v_pk_fma_f32 v[172:173], v[88:89], v[232:233], v[172:173]
	v_mov_b32_dpp v235, v165 row_ror:15 row_mask:0xf bank_mask:0xf
	v_pk_add_f32 v[172:173], v[96:97], v[172:173]
	s_nop 0
	v_mul_f32_e32 v174, 0xbfb8aa3b, v172
	v_exp_f32_e32 v174, v174
	s_nop 0
	v_add_f32_e32 v174, 1.0, v174
	v_rcp_f32_e32 v232, v174
	v_mul_f32_e32 v174, 0xbfb8aa3b, v173
	v_exp_f32_e32 v174, v174
	s_nop 0
	v_add_f32_e32 v174, 1.0, v174
	v_rcp_f32_e32 v233, v174
	v_lshlrev_b32_e32 v174, 16, v175
	v_and_b32_e32 v175, 0xffff0000, v175
	v_pk_mul_f32 v[172:173], v[172:173], v[232:233]
	s_nop 0
	v_pk_mul_f32 v[156:157], v[156:157], v[172:173]
	v_lshlrev_b32_e32 v172, 16, v231
	v_and_b32_e32 v173, 0xffff0000, v231
	v_pk_mul_f32 v[172:173], v[102:103], v[172:173]
	v_lshlrev_b32_e32 v232, 16, v252
	v_and_b32_e32 v233, 0xffff0000, v252
	v_pk_fma_f32 v[172:173], v[94:95], v[174:175], v[172:173]
	v_mov_b32_dpp v231, v170 row_ror:1 row_mask:0xf bank_mask:0xf
	v_pk_fma_f32 v[172:173], v[90:91], v[232:233], v[172:173]
	v_mov_b32_dpp v232, v171 row_ror:1 row_mask:0xf bank_mask:0xf
	v_pk_add_f32 v[172:173], v[98:99], v[172:173]
	v_or_b32_e32 v233, 16, v226
	v_mul_f32_e32 v174, 0xbfb8aa3b, v172
	v_mul_f32_e32 v175, 0xbfb8aa3b, v173
	v_exp_f32_e32 v174, v174
	v_exp_f32_e32 v175, v175
	s_waitcnt lgkmcnt(0)
	v_cndmask_b32_e64 v242, v232, v242, s[4:5]
	v_add_f32_e32 v174, 1.0, v174
	v_add_f32_e32 v175, 1.0, v175
	v_rcp_f32_e32 v174, v174
	v_rcp_f32_e32 v175, v175
	s_nop 0
	v_pk_mul_f32 v[172:173], v[172:173], v[174:175]
	v_mov_b32_dpp v174, v168 row_ror:1 row_mask:0xf bank_mask:0xf
	v_pk_mul_f32 v[172:173], v[158:159], v[172:173]
	v_cvt_pk_bf16_f32 v158, v160, v161
	v_cvt_pk_bf16_f32 v161, v172, v173
	v_mov_b64_e32 v[172:173], s[16:17]
	v_cvt_pk_bf16_f32 v160, v156, v157
	v_mad_i64_i32 v[156:157], s[2:3], v226, s26, v[172:173]
	v_cvt_pk_bf16_f32 v159, v162, v163
	v_lshl_add_u64 v[156:157], v[156:157], 0, v[204:205]
	global_store_dwordx4 v[156:157], v[158:161], off
	v_lshlrev_b32_e32 v162, 16, v168
	v_and_b32_e32 v163, 0xffff0000, v168
	s_waitcnt lgkmcnt(0)
	v_cndmask_b32_e64 v159, v174, v239, s[4:5]
	v_lshlrev_b32_e32 v158, 16, v159
	v_and_b32_e32 v159, 0xffff0000, v159
	v_cndmask_b32_e64 v161, v243, v234, s[6:7]
	v_pk_mul_f32 v[158:159], v[120:121], v[158:159]
	v_lshlrev_b32_e32 v160, 16, v161
	v_and_b32_e32 v161, 0xffff0000, v161
	v_pk_fma_f32 v[158:159], v[112:113], v[162:163], v[158:159]
	v_mov_b32_dpp v175, v169 row_ror:1 row_mask:0xf bank_mask:0xf
	v_pk_fma_f32 v[158:159], v[108:109], v[160:161], v[158:159]
	v_cndmask_b32_e64 v239, v244, v235, s[6:7]
	v_pk_add_f32 v[158:159], v[116:117], v[158:159]
	v_lshlrev_b32_e32 v162, 16, v169
	v_mul_f32_e32 v160, 0xbfb8aa3b, v158
	v_mul_f32_e32 v161, 0xbfb8aa3b, v159
	v_exp_f32_e32 v160, v160
	v_exp_f32_e32 v161, v161
	s_waitcnt lgkmcnt(0)
	v_cndmask_b32_e64 v238, v175, v240, s[4:5]
	v_and_b32_e32 v163, 0xffff0000, v169
	v_add_f32_e32 v160, 1.0, v160
	v_add_f32_e32 v161, 1.0, v161
	v_rcp_f32_e32 v160, v160
	v_rcp_f32_e32 v161, v161
	v_cndmask_b32_e64 v240, v231, v241, s[4:5]
	v_cndmask_b32_e64 v241, v245, v236, s[6:7]
	v_cndmask_b32_e64 v243, v246, v237, s[6:7]
	v_pk_mul_f32 v[158:159], v[158:159], v[160:161]
	v_lshlrev_b32_e32 v160, 16, v239
	v_pk_mul_f32 v[148:149], v[148:149], v[158:159]
	v_lshlrev_b32_e32 v158, 16, v238
	v_and_b32_e32 v159, 0xffff0000, v238
	v_pk_mul_f32 v[158:159], v[122:123], v[158:159]
	v_and_b32_e32 v161, 0xffff0000, v239
	v_pk_fma_f32 v[158:159], v[114:115], v[162:163], v[158:159]
	v_lshlrev_b32_e32 v162, 16, v170
	v_pk_fma_f32 v[158:159], v[110:111], v[160:161], v[158:159]
	v_and_b32_e32 v163, 0xffff0000, v170
	v_pk_add_f32 v[158:159], v[118:119], v[158:159]
	v_cvt_pk_bf16_f32 v148, v148, v149
	v_mul_f32_e32 v160, 0xbfb8aa3b, v158
	v_mul_f32_e32 v161, 0xbfb8aa3b, v159
	v_exp_f32_e32 v160, v160
	v_exp_f32_e32 v161, v161
	v_mov_b32_dpp v168, v153 row_ror:15 row_mask:0xf bank_mask:0xf
	v_mov_b32_dpp v169, v154 row_ror:15 row_mask:0xf bank_mask:0xf
	v_add_f32_e32 v160, 1.0, v160
	v_add_f32_e32 v161, 1.0, v161
	v_rcp_f32_e32 v160, v160
	v_rcp_f32_e32 v161, v161
	v_mov_b32_dpp v170, v155 row_ror:15 row_mask:0xf bank_mask:0xf
	v_pk_mul_f32 v[158:159], v[158:159], v[160:161]
	s_nop 0
	v_pk_mul_f32 v[150:151], v[150:151], v[158:159]
	v_lshlrev_b32_e32 v158, 16, v240
	v_and_b32_e32 v159, 0xffff0000, v240
	v_pk_mul_f32 v[158:159], v[100:101], v[158:159]
	v_lshlrev_b32_e32 v160, 16, v241
	v_and_b32_e32 v161, 0xffff0000, v241
	v_pk_fma_f32 v[158:159], v[92:93], v[162:163], v[158:159]
	v_lshlrev_b32_e32 v162, 16, v171
	v_pk_fma_f32 v[158:159], v[88:89], v[160:161], v[158:159]
	v_and_b32_e32 v163, 0xffff0000, v171
	v_pk_add_f32 v[158:159], v[96:97], v[158:159]
	v_cvt_pk_bf16_f32 v149, v150, v151
	v_mul_f32_e32 v160, 0xbfb8aa3b, v158
	v_mul_f32_e32 v161, 0xbfb8aa3b, v159
	v_exp_f32_e32 v160, v160
	v_exp_f32_e32 v161, v161
	v_add_f32_e32 v160, 1.0, v160
	v_add_f32_e32 v161, 1.0, v161
	v_rcp_f32_e32 v160, v160
	v_rcp_f32_e32 v161, v161
	s_nop 0
	v_pk_mul_f32 v[158:159], v[158:159], v[160:161]
	s_nop 0
	v_pk_mul_f32 v[144:145], v[144:145], v[158:159]
	v_lshlrev_b32_e32 v158, 16, v242
	v_and_b32_e32 v159, 0xffff0000, v242
	v_pk_mul_f32 v[158:159], v[102:103], v[158:159]
	v_lshlrev_b32_e32 v160, 16, v243
	v_and_b32_e32 v161, 0xffff0000, v243
	v_pk_fma_f32 v[158:159], v[94:95], v[162:163], v[158:159]
	v_mov_b32_dpp v163, v152 row_ror:15 row_mask:0xf bank_mask:0xf
	v_pk_fma_f32 v[158:159], v[90:91], v[160:161], v[158:159]
	v_cvt_pk_bf16_f32 v150, v144, v145
	v_pk_add_f32 v[158:159], v[98:99], v[158:159]
	v_mad_i64_i32 v[144:145], s[2:3], v233, s26, v[172:173]
	v_mul_f32_e32 v160, 0xbfb8aa3b, v158
	v_mul_f32_e32 v161, 0xbfb8aa3b, v159
	v_exp_f32_e32 v160, v160
	v_exp_f32_e32 v161, v161
	s_waitcnt lgkmcnt(0)
	v_cndmask_b32_e64 v233, v237, v170, s[6:7]
	v_or_b32_e32 v162, 32, v226
	v_add_f32_e32 v160, 1.0, v160
	v_add_f32_e32 v161, 1.0, v161
	v_rcp_f32_e32 v160, v160
	v_rcp_f32_e32 v161, v161
	s_nop 0
	v_pk_mul_f32 v[158:159], v[158:159], v[160:161]
	s_nop 0
	v_pk_mul_f32 v[146:147], v[146:147], v[158:159]
	v_mov_b32_dpp v158, v164 row_ror:1 row_mask:0xf bank_mask:0xf
	v_cvt_pk_bf16_f32 v151, v146, v147
	v_lshl_add_u64 v[146:147], v[144:145], 0, v[204:205]
	global_store_dwordx4 v[146:147], v[148:151], off
	v_mov_b32_dpp v159, v165 row_ror:1 row_mask:0xf bank_mask:0xf
	s_waitcnt lgkmcnt(0)
	v_cndmask_b32_e64 v145, v158, v174, s[4:5]
	v_lshlrev_b32_e32 v144, 16, v145
	v_and_b32_e32 v145, 0xffff0000, v145
	v_cndmask_b32_e64 v149, v234, v163, s[6:7]
	v_pk_mul_f32 v[144:145], v[120:121], v[144:145]
	v_lshlrev_b32_e32 v150, 16, v164
	v_and_b32_e32 v151, 0xffff0000, v164
	v_lshlrev_b32_e32 v148, 16, v149
	v_and_b32_e32 v149, 0xffff0000, v149
	v_pk_fma_f32 v[144:145], v[112:113], v[150:151], v[144:145]
	s_waitcnt lgkmcnt(0)
	v_cndmask_b32_e64 v171, v159, v175, s[4:5]
	v_pk_fma_f32 v[144:145], v[108:109], v[148:149], v[144:145]
	v_cndmask_b32_e64 v174, v235, v168, s[6:7]
	v_pk_add_f32 v[144:145], v[116:117], v[144:145]
	v_lshlrev_b32_e32 v150, 16, v165
	v_mul_f32_e32 v148, 0xbfb8aa3b, v144
	v_mul_f32_e32 v149, 0xbfb8aa3b, v145
	v_exp_f32_e32 v148, v148
	v_exp_f32_e32 v149, v149
	v_and_b32_e32 v151, 0xffff0000, v165
	v_mov_b32_dpp v160, v166 row_ror:1 row_mask:0xf bank_mask:0xf
	v_add_f32_e32 v148, 1.0, v148
	v_add_f32_e32 v149, 1.0, v149
	v_rcp_f32_e32 v148, v148
	v_rcp_f32_e32 v149, v149
	s_waitcnt lgkmcnt(0)
	v_cndmask_b32_e64 v175, v160, v231, s[4:5]
	v_cndmask_b32_e64 v231, v236, v169, s[6:7]
	v_mov_b32_dpp v161, v167 row_ror:1 row_mask:0xf bank_mask:0xf
	v_pk_mul_f32 v[144:145], v[144:145], v[148:149]
	v_lshlrev_b32_e32 v148, 16, v174
	v_pk_mul_f32 v[140:141], v[140:141], v[144:145]
	v_lshlrev_b32_e32 v144, 16, v171
	v_and_b32_e32 v145, 0xffff0000, v171
	v_pk_mul_f32 v[144:145], v[122:123], v[144:145]
	v_and_b32_e32 v149, 0xffff0000, v174
	v_pk_fma_f32 v[144:145], v[114:115], v[150:151], v[144:145]
	v_lshlrev_b32_e32 v150, 16, v166
	v_pk_fma_f32 v[144:145], v[110:111], v[148:149], v[144:145]
	v_and_b32_e32 v151, 0xffff0000, v166
	v_pk_add_f32 v[144:145], v[118:119], v[144:145]
	s_waitcnt lgkmcnt(0)
	v_cndmask_b32_e64 v232, v161, v232, s[4:5]
	v_mul_f32_e32 v148, 0xbfb8aa3b, v144
	v_mul_f32_e32 v149, 0xbfb8aa3b, v145
	v_exp_f32_e32 v148, v148
	v_exp_f32_e32 v149, v149
	v_or_b32_e32 v164, s12, v221
	v_add_f32_e32 v148, 1.0, v148
	v_add_f32_e32 v149, 1.0, v149
	v_rcp_f32_e32 v148, v148
	v_rcp_f32_e32 v149, v149
	s_nop 0
	v_pk_mul_f32 v[144:145], v[144:145], v[148:149]
	s_nop 0
	v_pk_mul_f32 v[142:143], v[142:143], v[144:145]
	v_lshlrev_b32_e32 v144, 16, v175
	v_and_b32_e32 v145, 0xffff0000, v175
	v_pk_mul_f32 v[144:145], v[100:101], v[144:145]
	v_lshlrev_b32_e32 v148, 16, v231
	v_and_b32_e32 v149, 0xffff0000, v231
	v_pk_fma_f32 v[144:145], v[92:93], v[150:151], v[144:145]
	v_lshlrev_b32_e32 v150, 16, v167
	v_pk_fma_f32 v[144:145], v[88:89], v[148:149], v[144:145]
	v_and_b32_e32 v151, 0xffff0000, v167
	v_pk_add_f32 v[144:145], v[96:97], v[144:145]
	s_nop 0
	v_mul_f32_e32 v148, 0xbfb8aa3b, v144
	v_mul_f32_e32 v149, 0xbfb8aa3b, v145
	v_exp_f32_e32 v148, v148
	v_exp_f32_e32 v149, v149
	v_add_f32_e32 v148, 1.0, v148
	v_add_f32_e32 v149, 1.0, v149
	v_rcp_f32_e32 v148, v148
	v_rcp_f32_e32 v149, v149
	s_nop 0
	v_pk_mul_f32 v[144:145], v[144:145], v[148:149]
	s_nop 0
	v_pk_mul_f32 v[144:145], v[136:137], v[144:145]
	v_lshlrev_b32_e32 v136, 16, v232
	v_and_b32_e32 v137, 0xffff0000, v232
	v_pk_mul_f32 v[136:137], v[102:103], v[136:137]
	v_lshlrev_b32_e32 v148, 16, v233
	v_and_b32_e32 v149, 0xffff0000, v233
	v_pk_fma_f32 v[136:137], v[94:95], v[150:151], v[136:137]
	v_cndmask_b32_e64 v150, v169, v228, s[6:7]
	v_pk_fma_f32 v[136:137], v[90:91], v[148:149], v[136:137]
	s_nop 0
	v_pk_add_f32 v[136:137], v[98:99], v[136:137]
	s_nop 0
	v_mul_f32_e32 v148, 0xbfb8aa3b, v136
	v_mul_f32_e32 v149, 0xbfb8aa3b, v137
	v_exp_f32_e32 v148, v148
	v_exp_f32_e32 v149, v149
	v_add_f32_e32 v148, 1.0, v148
	v_add_f32_e32 v149, 1.0, v149
	v_rcp_f32_e32 v148, v148
	v_rcp_f32_e32 v149, v149
	s_nop 0
	v_pk_mul_f32 v[136:137], v[136:137], v[148:149]
	s_nop 0
	v_pk_mul_f32 v[148:149], v[138:139], v[136:137]
	v_cvt_pk_bf16_f32 v136, v140, v141
	v_mad_i64_i32 v[140:141], s[2:3], v162, s26, v[172:173]
	v_cvt_pk_bf16_f32 v137, v142, v143
	v_cvt_pk_bf16_f32 v138, v144, v145
	v_cvt_pk_bf16_f32 v139, v148, v149
	v_lshl_add_u64 v[148:149], v[140:141], 0, v[204:205]
	global_store_dwordx4 v[148:149], v[136:139], off
	ds_bpermute_b32 v136, v193, v152
	ds_bpermute_b32 v137, v193, v153
	v_mov_b32_dpp v138, v154 row_ror:1 row_mask:0xf bank_mask:0xf
	v_mov_b32_dpp v139, v155 row_ror:1 row_mask:0xf bank_mask:0xf
	v_cndmask_b32_e64 v141, v163, v230, s[6:7]
	s_waitcnt lgkmcnt(0)
	v_cndmask_b32_e64 v140, v136, v158, s[4:5]
	s_waitcnt lgkmcnt(0)
	v_cndmask_b32_e64 v143, v137, v159, s[4:5]
	v_lshlrev_b32_e32 v136, 16, v140
	v_and_b32_e32 v137, 0xffff0000, v140
	s_waitcnt lgkmcnt(0)
	v_cndmask_b32_e64 v145, v138, v160, s[4:5]
	s_waitcnt lgkmcnt(0)
	v_cndmask_b32_e64 v151, v139, v161, s[4:5]
	v_lshlrev_b32_e32 v138, 16, v141
	v_and_b32_e32 v139, 0xffff0000, v141
	v_pk_mul_f32 v[136:137], v[120:121], v[136:137]
	v_lshlrev_b32_e32 v140, 16, v152
	v_and_b32_e32 v141, 0xffff0000, v152
	v_pk_fma_f32 v[136:137], v[112:113], v[140:141], v[136:137]
	v_cndmask_b32_e64 v144, v168, v229, s[6:7]
	v_pk_fma_f32 v[136:137], v[108:109], v[138:139], v[136:137]
	v_lshlrev_b32_e32 v140, 16, v153
	v_pk_add_f32 v[136:137], v[116:117], v[136:137]
	v_and_b32_e32 v141, 0xffff0000, v153
	v_mul_f32_e32 v138, 0xbfb8aa3b, v136
	v_mul_f32_e32 v139, 0xbfb8aa3b, v137
	v_exp_f32_e32 v138, v138
	v_exp_f32_e32 v139, v139
	v_cndmask_b32_e64 v158, v170, v227, s[6:7]
	v_or_b32_e32 v142, 48, v226
	v_add_f32_e32 v138, 1.0, v138
	v_add_f32_e32 v139, 1.0, v139
	v_rcp_f32_e32 v138, v138
	v_rcp_f32_e32 v139, v139
	s_nop 0
	v_pk_mul_f32 v[136:137], v[136:137], v[138:139]
	s_nop 0
	v_pk_mul_f32 v[132:133], v[132:133], v[136:137]
	v_lshlrev_b32_e32 v136, 16, v143
	v_and_b32_e32 v137, 0xffff0000, v143
	v_pk_mul_f32 v[136:137], v[122:123], v[136:137]
	v_lshlrev_b32_e32 v138, 16, v144
	v_and_b32_e32 v139, 0xffff0000, v144
	v_pk_fma_f32 v[136:137], v[114:115], v[140:141], v[136:137]
	v_lshlrev_b32_e32 v140, 16, v154
	v_pk_fma_f32 v[136:137], v[110:111], v[138:139], v[136:137]
	v_and_b32_e32 v141, 0xffff0000, v154
	v_pk_add_f32 v[136:137], v[118:119], v[136:137]
	s_nop 0
	v_mul_f32_e32 v138, 0xbfb8aa3b, v136
	v_mul_f32_e32 v139, 0xbfb8aa3b, v137
	v_exp_f32_e32 v138, v138
	v_exp_f32_e32 v139, v139
	v_add_f32_e32 v138, 1.0, v138
	v_add_f32_e32 v139, 1.0, v139
	v_rcp_f32_e32 v138, v138
	v_rcp_f32_e32 v139, v139
	s_nop 0
	v_pk_mul_f32 v[136:137], v[136:137], v[138:139]
	s_nop 0
	v_pk_mul_f32 v[134:135], v[134:135], v[136:137]
	v_lshlrev_b32_e32 v136, 16, v145
	v_and_b32_e32 v137, 0xffff0000, v145
	v_pk_mul_f32 v[136:137], v[100:101], v[136:137]
	v_lshlrev_b32_e32 v138, 16, v150
	v_and_b32_e32 v139, 0xffff0000, v150
	v_pk_fma_f32 v[136:137], v[92:93], v[140:141], v[136:137]
	v_lshlrev_b32_e32 v140, 16, v155
	v_pk_fma_f32 v[136:137], v[88:89], v[138:139], v[136:137]
	v_and_b32_e32 v141, 0xffff0000, v155
	v_pk_add_f32 v[136:137], v[96:97], v[136:137]
	s_nop 0
	v_mul_f32_e32 v138, 0xbfb8aa3b, v136
	v_mul_f32_e32 v139, 0xbfb8aa3b, v137
	v_exp_f32_e32 v138, v138
	v_exp_f32_e32 v139, v139
	v_add_f32_e32 v138, 1.0, v138
	v_add_f32_e32 v139, 1.0, v139
	v_rcp_f32_e32 v138, v138
	v_rcp_f32_e32 v139, v139
	s_nop 0
	v_pk_mul_f32 v[136:137], v[136:137], v[138:139]
	s_nop 0
	v_pk_mul_f32 v[136:137], v[128:129], v[136:137]
	v_lshlrev_b32_e32 v128, 16, v151
	v_and_b32_e32 v129, 0xffff0000, v151
	v_pk_mul_f32 v[128:129], v[102:103], v[128:129]
	v_lshlrev_b32_e32 v138, 16, v158
	v_and_b32_e32 v139, 0xffff0000, v158
	v_pk_fma_f32 v[128:129], v[94:95], v[140:141], v[128:129]
	s_nop 0
	v_pk_fma_f32 v[128:129], v[90:91], v[138:139], v[128:129]
	s_nop 0
	v_pk_add_f32 v[128:129], v[98:99], v[128:129]
	s_nop 0
	v_mul_f32_e32 v138, 0xbfb8aa3b, v128
	v_mul_f32_e32 v139, 0xbfb8aa3b, v129
	v_exp_f32_e32 v138, v138
	v_exp_f32_e32 v139, v139
	v_add_f32_e32 v138, 1.0, v138
	v_add_f32_e32 v139, 1.0, v139
	v_rcp_f32_e32 v138, v138
	v_rcp_f32_e32 v139, v139
	s_nop 0
	v_pk_mul_f32 v[128:129], v[128:129], v[138:139]
	s_nop 0
	v_pk_mul_f32 v[138:139], v[130:131], v[128:129]
	v_cvt_pk_bf16_f32 v128, v132, v133
	v_mad_i64_i32 v[132:133], s[2:3], v142, s26, v[172:173]
	v_cvt_pk_bf16_f32 v129, v134, v135
	v_cvt_pk_bf16_f32 v130, v136, v137
	v_cvt_pk_bf16_f32 v131, v138, v139
	v_lshl_add_u64 v[144:145], v[132:133], 0, v[204:205]
	global_store_dwordx4 v[144:145], v[128:131], off
	s_nop 1
	v_mad_i64_i32 v[128:129], s[2:3], v164, s26, v[208:209]
	v_lshl_add_u64 v[150:151], v[128:129], 0, v[204:205]
	v_add_co_u32_e32 v152, vcc, s21, v150
	s_mul_hi_i32 s2, s12, 0x2c00
	s_nop 0
	v_addc_co_u32_e32 v153, vcc, 0, v151, vcc
	v_add_co_u32_e32 v154, vcc, s22, v150
	global_load_dwordx4 v[140:143], v[150:151], off
	global_load_dwordx4 v[136:139], v[152:153], off
	v_addc_co_u32_e32 v155, vcc, 0, v151, vcc
	v_add_co_u32_e32 v158, vcc, s23, v150
	s_cselect_b64 s[22:23], -1, 0
	s_add_i32 s1, s1, 0x160000
	s_add_u32 s0, s10, s1
	s_addc_u32 s1, s11, s2
	s_and_b64 s[2:3], s[22:23], exec
	v_addc_co_u32_e32 v159, vcc, 0, v151, vcc
	s_cselect_b32 s2, 0, 0xffffd400
	s_cselect_b32 s3, 0, -1
	s_cmp_eq_u32 s15, s13
	s_cselect_b64 vcc, -1, 0
	v_lshl_add_u64 v[160:161], s[0:1], 0, v[204:205]
	s_and_b64 s[0:1], vcc, exec
	s_cselect_b32 s72, 0, 0xb0000
	v_lshl_add_u64 v[162:163], v[160:161], 0, s[2:3]
	v_lshl_add_u64 v[160:161], v[160:161], 0, s[72:73]
	global_load_dwordx4 v[166:169], v[162:163], off
	global_load_dwordx4 v[226:229], v[160:161], off
	global_load_dwordx4 v[132:135], v[154:155], off
	global_load_dwordx4 v[128:131], v[158:159], off
	s_waitcnt vmcnt(5)
	v_mov_b32_dpp v175, v140 row_ror:15 row_mask:0xf bank_mask:0xf
	v_mov_b32_dpp v208, v141 row_ror:15 row_mask:0xf bank_mask:0xf
	v_mov_b32_dpp v209, v142 row_ror:15 row_mask:0xf bank_mask:0xf
	s_waitcnt vmcnt(4)
	v_mov_b32_dpp v231, v136 row_ror:15 row_mask:0xf bank_mask:0xf
	v_mov_b32_dpp v232, v137 row_ror:15 row_mask:0xf bank_mask:0xf
	v_mov_b32_dpp v233, v138 row_ror:15 row_mask:0xf bank_mask:0xf
	v_mov_b32_dpp v230, v143 row_ror:15 row_mask:0xf bank_mask:0xf
	v_mov_b32_dpp v234, v139 row_ror:15 row_mask:0xf bank_mask:0xf
	s_waitcnt lgkmcnt(0)
	v_cndmask_b32_e64 v175, v175, v231, s[6:7]
	s_waitcnt lgkmcnt(0)
	v_cndmask_b32_e64 v237, v208, v232, s[6:7]
	s_waitcnt lgkmcnt(0)
	v_cndmask_b32_e64 v239, v209, v233, s[6:7]
	v_lshlrev_b32_e32 v208, 16, v140
	v_and_b32_e32 v209, 0xffff0000, v140
	s_waitcnt lgkmcnt(0)
	v_cndmask_b32_e64 v230, v230, v234, s[6:7]
	s_waitcnt vmcnt(3)
	v_cndmask_b32_e64 v170, v168, 0, s[22:23]
	s_waitcnt vmcnt(2)
	v_cndmask_b32_e64 v168, v226, 0, vcc
	v_mov_b32_dpp v226, v140 row_ror:1 row_mask:0xf bank_mask:0xf
	v_cndmask_b32_e64 v171, v167, 0, s[22:23]
	v_cndmask_b32_e64 v174, v166, 0, s[22:23]
	v_cndmask_b32_e64 v166, v228, 0, vcc
	v_cndmask_b32_e64 v167, v227, 0, vcc
	v_mov_b32_dpp v227, v141 row_ror:1 row_mask:0xf bank_mask:0xf
	v_mov_b32_dpp v228, v142 row_ror:1 row_mask:0xf bank_mask:0xf
	s_waitcnt lgkmcnt(0)
	v_cndmask_b32_e64 v235, v226, v174, s[4:5]
	v_lshlrev_b32_e32 v174, 16, v175
	v_and_b32_e32 v175, 0xffff0000, v175
	s_waitcnt lgkmcnt(0)
	v_cndmask_b32_e64 v236, v227, v171, s[4:5]
	s_waitcnt lgkmcnt(0)
	v_cndmask_b32_e64 v238, v228, v170, s[4:5]
	v_lshlrev_b32_e32 v170, 16, v235
	v_and_b32_e32 v171, 0xffff0000, v235
	v_pk_mul_f32 v[170:171], v[120:121], v[170:171]
	v_cndmask_b32_e64 v165, v229, 0, vcc
	v_pk_fma_f32 v[170:171], v[112:113], v[208:209], v[170:171]
	v_mov_b32_dpp v229, v143 row_ror:1 row_mask:0xf bank_mask:0xf
	v_pk_fma_f32 v[170:171], v[108:109], v[174:175], v[170:171]
	v_cndmask_b32_e64 v169, v169, 0, s[22:23]
	v_pk_add_f32 v[170:171], v[116:117], v[170:171]
	s_waitcnt lgkmcnt(0)
	v_cndmask_b32_e64 v169, v229, v169, s[4:5]
	v_mul_f32_e32 v140, 0xbfb8aa3b, v170
	v_exp_f32_e32 v140, v140
	s_nop 0
	v_add_f32_e32 v140, 1.0, v140
	v_rcp_f32_e32 v174, v140
	v_mul_f32_e32 v140, 0xbfb8aa3b, v171
	v_exp_f32_e32 v140, v140
	s_nop 0
	v_add_f32_e32 v140, 1.0, v140
	v_rcp_f32_e32 v175, v140
	v_lshlrev_b32_e32 v140, 16, v141
	v_and_b32_e32 v141, 0xffff0000, v141
	v_pk_mul_f32 v[170:171], v[170:171], v[174:175]
	s_nop 0
	v_pk_mul_f32 v[124:125], v[124:125], v[170:171]
	v_lshlrev_b32_e32 v170, 16, v236
	v_and_b32_e32 v171, 0xffff0000, v236
	v_pk_mul_f32 v[170:171], v[122:123], v[170:171]
	v_lshlrev_b32_e32 v174, 16, v237
	v_and_b32_e32 v175, 0xffff0000, v237
	v_pk_fma_f32 v[140:141], v[114:115], v[140:141], v[170:171]
	s_nop 0
	v_pk_fma_f32 v[140:141], v[110:111], v[174:175], v[140:141]
	v_lshlrev_b32_e32 v174, 16, v142
	v_pk_add_f32 v[140:141], v[118:119], v[140:141]
	v_and_b32_e32 v175, 0xffff0000, v142
	v_mul_f32_e32 v170, 0xbfb8aa3b, v140
	v_mul_f32_e32 v171, 0xbfb8aa3b, v141
	v_exp_f32_e32 v170, v170
	v_exp_f32_e32 v171, v171
	v_add_f32_e32 v170, 1.0, v170
	v_add_f32_e32 v171, 1.0, v171
	v_rcp_f32_e32 v170, v170
	v_rcp_f32_e32 v171, v171
	s_nop 0
	v_pk_mul_f32 v[140:141], v[140:141], v[170:171]
	s_nop 0
	v_pk_mul_f32 v[126:127], v[126:127], v[140:141]
	v_lshlrev_b32_e32 v140, 16, v238
	v_and_b32_e32 v141, 0xffff0000, v238
	v_pk_mul_f32 v[140:141], v[100:101], v[140:141]
	v_lshlrev_b32_e32 v170, 16, v239
	v_and_b32_e32 v171, 0xffff0000, v239
	v_pk_fma_f32 v[140:141], v[92:93], v[174:175], v[140:141]
	s_waitcnt vmcnt(1)
	v_mov_b32_dpp v174, v134 row_ror:15 row_mask:0xf bank_mask:0xf
	v_pk_fma_f32 v[140:141], v[88:89], v[170:171], v[140:141]
	v_mov_b32_dpp v175, v135 row_ror:15 row_mask:0xf bank_mask:0xf
	v_pk_add_f32 v[140:141], v[96:97], v[140:141]
	s_nop 0
	v_mul_f32_e32 v142, 0xbfb8aa3b, v140
	v_exp_f32_e32 v142, v142
	s_nop 0
	v_add_f32_e32 v142, 1.0, v142
	v_rcp_f32_e32 v170, v142
	v_mul_f32_e32 v142, 0xbfb8aa3b, v141
	v_exp_f32_e32 v142, v142
	s_nop 0
	v_add_f32_e32 v142, 1.0, v142
	v_rcp_f32_e32 v171, v142
	v_lshlrev_b32_e32 v142, 16, v143
	v_and_b32_e32 v143, 0xffff0000, v143
	v_pk_mul_f32 v[140:141], v[140:141], v[170:171]
	s_nop 0
	v_pk_mul_f32 v[140:141], v[104:105], v[140:141]
	v_lshlrev_b32_e32 v104, 16, v169
	v_and_b32_e32 v105, 0xffff0000, v169
	v_pk_mul_f32 v[104:105], v[102:103], v[104:105]
	v_lshlrev_b32_e32 v170, 16, v230
	v_and_b32_e32 v171, 0xffff0000, v230
	v_pk_fma_f32 v[104:105], v[94:95], v[142:143], v[104:105]
	v_or_b32_e32 v169, 16, v164
	v_pk_fma_f32 v[104:105], v[90:91], v[170:171], v[104:105]
	v_mov_b32_dpp v170, v132 row_ror:15 row_mask:0xf bank_mask:0xf
	v_pk_add_f32 v[104:105], v[98:99], v[104:105]
	v_mov_b32_dpp v171, v133 row_ror:15 row_mask:0xf bank_mask:0xf
	v_mul_f32_e32 v142, 0xbfb8aa3b, v104
	v_mul_f32_e32 v143, 0xbfb8aa3b, v105
	v_exp_f32_e32 v142, v142
	v_exp_f32_e32 v143, v143
	s_waitcnt lgkmcnt(0)
	v_cndmask_b32_e64 v209, v232, v171, s[6:7]
	v_add_f32_e32 v142, 1.0, v142
	v_add_f32_e32 v143, 1.0, v143
	v_rcp_f32_e32 v142, v142
	v_rcp_f32_e32 v143, v143
	s_nop 0
	v_pk_mul_f32 v[104:105], v[104:105], v[142:143]
	s_nop 0
	v_pk_mul_f32 v[142:143], v[106:107], v[104:105]
	v_cvt_pk_bf16_f32 v106, v140, v141
	v_mov_b32_dpp v140, v136 row_ror:1 row_mask:0xf bank_mask:0xf
	v_cvt_pk_bf16_f32 v104, v124, v125
	v_mad_i64_i32 v[124:125], s[0:1], v164, s26, v[172:173]
	v_cvt_pk_bf16_f32 v105, v126, v127
	v_cvt_pk_bf16_f32 v107, v142, v143
	v_lshl_add_u64 v[124:125], v[124:125], 0, v[204:205]
	global_store_dwordx4 v[124:125], v[104:107], off
	v_lshlrev_b32_e32 v126, 16, v136
	v_and_b32_e32 v127, 0xffff0000, v136
	s_waitcnt lgkmcnt(0)
	v_cndmask_b32_e64 v105, v140, v226, s[4:5]
	v_lshlrev_b32_e32 v104, 16, v105
	v_and_b32_e32 v105, 0xffff0000, v105
	v_cndmask_b32_e64 v107, v231, v170, s[6:7]
	v_pk_mul_f32 v[104:105], v[120:121], v[104:105]
	v_lshlrev_b32_e32 v106, 16, v107
	v_and_b32_e32 v107, 0xffff0000, v107
	v_pk_fma_f32 v[104:105], v[112:113], v[126:127], v[104:105]
	v_mov_b32_dpp v141, v137 row_ror:1 row_mask:0xf bank_mask:0xf
	v_pk_fma_f32 v[104:105], v[108:109], v[106:107], v[104:105]
	v_lshlrev_b32_e32 v126, 16, v137
	v_pk_add_f32 v[104:105], v[116:117], v[104:105]
	v_and_b32_e32 v127, 0xffff0000, v137
	v_mul_f32_e32 v106, 0xbfb8aa3b, v104
	v_mul_f32_e32 v107, 0xbfb8aa3b, v105
	v_exp_f32_e32 v106, v106
	v_exp_f32_e32 v107, v107
	s_waitcnt lgkmcnt(0)
	v_cndmask_b32_e64 v208, v141, v227, s[4:5]
	v_mov_b32_dpp v142, v138 row_ror:1 row_mask:0xf bank_mask:0xf
	v_add_f32_e32 v106, 1.0, v106
	v_add_f32_e32 v107, 1.0, v107
	v_rcp_f32_e32 v106, v106
	v_rcp_f32_e32 v107, v107
	s_waitcnt lgkmcnt(0)
	v_cndmask_b32_e64 v226, v142, v228, s[4:5]
	v_cndmask_b32_e64 v227, v233, v174, s[6:7]
	v_mov_b32_dpp v143, v139 row_ror:1 row_mask:0xf bank_mask:0xf
	v_pk_mul_f32 v[104:105], v[104:105], v[106:107]
	v_lshlrev_b32_e32 v106, 16, v209
	v_pk_mul_f32 v[84:85], v[84:85], v[104:105]
	v_lshlrev_b32_e32 v104, 16, v208
	v_and_b32_e32 v105, 0xffff0000, v208
	v_pk_mul_f32 v[104:105], v[122:123], v[104:105]
	v_and_b32_e32 v107, 0xffff0000, v209
	v_pk_fma_f32 v[104:105], v[114:115], v[126:127], v[104:105]
	v_lshlrev_b32_e32 v126, 16, v138
	v_pk_fma_f32 v[104:105], v[110:111], v[106:107], v[104:105]
	v_and_b32_e32 v127, 0xffff0000, v138
	v_pk_add_f32 v[104:105], v[118:119], v[104:105]
	s_waitcnt lgkmcnt(0)
	v_cndmask_b32_e64 v228, v143, v229, s[4:5]
	v_mul_f32_e32 v106, 0xbfb8aa3b, v104
	v_mul_f32_e32 v107, 0xbfb8aa3b, v105
	v_exp_f32_e32 v106, v106
	v_exp_f32_e32 v107, v107
	v_cndmask_b32_e64 v229, v234, v175, s[6:7]
	s_waitcnt vmcnt(1)
	v_mov_b32_dpp v136, v129 row_ror:15 row_mask:0xf bank_mask:0xf
	v_add_f32_e32 v106, 1.0, v106
	v_add_f32_e32 v107, 1.0, v107
	v_rcp_f32_e32 v106, v106
	v_rcp_f32_e32 v107, v107
	v_mov_b32_dpp v137, v130 row_ror:15 row_mask:0xf bank_mask:0xf
	v_mov_b32_dpp v138, v131 row_ror:15 row_mask:0xf bank_mask:0xf
	v_pk_mul_f32 v[104:105], v[104:105], v[106:107]
	s_nop 0
	v_pk_mul_f32 v[86:87], v[86:87], v[104:105]
	v_lshlrev_b32_e32 v104, 16, v226
	v_and_b32_e32 v105, 0xffff0000, v226
	v_pk_mul_f32 v[104:105], v[100:101], v[104:105]
	v_lshlrev_b32_e32 v106, 16, v227
	v_and_b32_e32 v107, 0xffff0000, v227
	v_pk_fma_f32 v[104:105], v[92:93], v[126:127], v[104:105]
	v_lshlrev_b32_e32 v126, 16, v139
	v_pk_fma_f32 v[104:105], v[88:89], v[106:107], v[104:105]
	v_and_b32_e32 v127, 0xffff0000, v139
	v_pk_add_f32 v[104:105], v[96:97], v[104:105]
	s_nop 0
	v_mul_f32_e32 v106, 0xbfb8aa3b, v104
	v_mul_f32_e32 v107, 0xbfb8aa3b, v105
	v_exp_f32_e32 v106, v106
	v_exp_f32_e32 v107, v107
	v_add_f32_e32 v106, 1.0, v106
	v_add_f32_e32 v107, 1.0, v107
	v_rcp_f32_e32 v106, v106
	v_rcp_f32_e32 v107, v107
	s_nop 0
	v_pk_mul_f32 v[104:105], v[104:105], v[106:107]
	s_nop 0
	v_pk_mul_f32 v[104:105], v[80:81], v[104:105]
	v_lshlrev_b32_e32 v80, 16, v228
	v_and_b32_e32 v81, 0xffff0000, v228
	v_pk_mul_f32 v[80:81], v[102:103], v[80:81]
	v_lshlrev_b32_e32 v106, 16, v229
	v_and_b32_e32 v107, 0xffff0000, v229
	v_pk_fma_f32 v[80:81], v[94:95], v[126:127], v[80:81]
	s_nop 0
	v_pk_fma_f32 v[80:81], v[90:91], v[106:107], v[80:81]
	s_nop 0
	v_pk_add_f32 v[80:81], v[98:99], v[80:81]
	s_nop 0
	v_mul_f32_e32 v106, 0xbfb8aa3b, v80
	v_mul_f32_e32 v107, 0xbfb8aa3b, v81
	v_exp_f32_e32 v106, v106
	v_exp_f32_e32 v107, v107
	v_add_f32_e32 v106, 1.0, v106
	v_add_f32_e32 v107, 1.0, v107
	v_rcp_f32_e32 v106, v106
	v_rcp_f32_e32 v107, v107
	s_nop 0
	v_pk_mul_f32 v[80:81], v[80:81], v[106:107]
	s_nop 0
	v_pk_mul_f32 v[106:107], v[82:83], v[80:81]
	v_cvt_pk_bf16_f32 v81, v86, v87
	v_mov_b32_dpp v86, v132 row_ror:1 row_mask:0xf bank_mask:0xf
	v_cvt_pk_bf16_f32 v83, v106, v107
	v_mov_b32_dpp v107, v128 row_ror:15 row_mask:0xf bank_mask:0xf
	v_cvt_pk_bf16_f32 v80, v84, v85
	v_mad_i64_i32 v[84:85], s[0:1], v169, s26, v[172:173]
	v_cvt_pk_bf16_f32 v82, v104, v105
	v_lshl_add_u64 v[126:127], v[84:85], 0, v[204:205]
	global_store_dwordx4 v[126:127], v[80:83], off
	v_lshlrev_b32_e32 v84, 16, v132
	v_and_b32_e32 v85, 0xffff0000, v132
	s_waitcnt lgkmcnt(0)
	v_cndmask_b32_e64 v81, v86, v140, s[4:5]
	v_lshlrev_b32_e32 v80, 16, v81
	v_and_b32_e32 v81, 0xffff0000, v81
	s_waitcnt lgkmcnt(0)
	v_cndmask_b32_e64 v83, v170, v107, s[6:7]
	v_pk_mul_f32 v[80:81], v[120:121], v[80:81]
	v_lshlrev_b32_e32 v82, 16, v83
	v_and_b32_e32 v83, 0xffff0000, v83
	v_pk_fma_f32 v[80:81], v[112:113], v[84:85], v[80:81]
	v_mov_b32_dpp v87, v133 row_ror:1 row_mask:0xf bank_mask:0xf
	v_pk_fma_f32 v[80:81], v[108:109], v[82:83], v[80:81]
	v_cndmask_b32_e64 v140, v171, v136, s[6:7]
	v_pk_add_f32 v[80:81], v[116:117], v[80:81]
	v_lshlrev_b32_e32 v84, 16, v133
	v_mul_f32_e32 v82, 0xbfb8aa3b, v80
	v_mul_f32_e32 v83, 0xbfb8aa3b, v81
	v_exp_f32_e32 v82, v82
	v_exp_f32_e32 v83, v83
	s_waitcnt lgkmcnt(0)
	v_cndmask_b32_e64 v139, v87, v141, s[4:5]
	v_and_b32_e32 v85, 0xffff0000, v133
	v_add_f32_e32 v82, 1.0, v82
	v_add_f32_e32 v83, 1.0, v83
	v_rcp_f32_e32 v82, v82
	v_rcp_f32_e32 v83, v83
	v_mov_b32_dpp v104, v134 row_ror:1 row_mask:0xf bank_mask:0xf
	v_mov_b32_dpp v105, v135 row_ror:1 row_mask:0xf bank_mask:0xf
	v_cndmask_b32_e64 v169, v175, v138, s[6:7]
	v_pk_mul_f32 v[80:81], v[80:81], v[82:83]
	v_lshlrev_b32_e32 v82, 16, v140
	v_pk_mul_f32 v[76:77], v[76:77], v[80:81]
	v_lshlrev_b32_e32 v80, 16, v139
	v_and_b32_e32 v81, 0xffff0000, v139
	v_pk_mul_f32 v[80:81], v[122:123], v[80:81]
	v_and_b32_e32 v83, 0xffff0000, v140
	v_pk_fma_f32 v[80:81], v[114:115], v[84:85], v[80:81]
	s_waitcnt lgkmcnt(0)
	v_cndmask_b32_e64 v141, v104, v142, s[4:5]
	v_pk_fma_f32 v[80:81], v[110:111], v[82:83], v[80:81]
	v_cndmask_b32_e64 v142, v174, v137, s[6:7]
	v_pk_add_f32 v[80:81], v[118:119], v[80:81]
	v_lshlrev_b32_e32 v84, 16, v134
	v_mul_f32_e32 v82, 0xbfb8aa3b, v80
	v_mul_f32_e32 v83, 0xbfb8aa3b, v81
	v_exp_f32_e32 v82, v82
	v_exp_f32_e32 v83, v83
	v_and_b32_e32 v85, 0xffff0000, v134
	s_waitcnt lgkmcnt(0)
	v_cndmask_b32_e64 v143, v105, v143, s[4:5]
	v_add_f32_e32 v82, 1.0, v82
	v_add_f32_e32 v83, 1.0, v83
	v_rcp_f32_e32 v82, v82
	v_rcp_f32_e32 v83, v83
	v_or_b32_e32 v106, 32, v164
	v_pk_mul_f32 v[80:81], v[80:81], v[82:83]
	s_nop 0
	v_pk_mul_f32 v[78:79], v[78:79], v[80:81]
	v_lshlrev_b32_e32 v80, 16, v141
	v_and_b32_e32 v81, 0xffff0000, v141
	v_pk_mul_f32 v[80:81], v[100:101], v[80:81]
	v_lshlrev_b32_e32 v82, 16, v142
	v_and_b32_e32 v83, 0xffff0000, v142
	v_pk_fma_f32 v[80:81], v[92:93], v[84:85], v[80:81]
	v_lshlrev_b32_e32 v84, 16, v135
	v_pk_fma_f32 v[80:81], v[88:89], v[82:83], v[80:81]
	v_and_b32_e32 v85, 0xffff0000, v135
	v_pk_add_f32 v[80:81], v[96:97], v[80:81]
	s_nop 0
	v_mul_f32_e32 v82, 0xbfb8aa3b, v80
	v_mul_f32_e32 v83, 0xbfb8aa3b, v81
	v_exp_f32_e32 v82, v82
	v_exp_f32_e32 v83, v83
	v_add_f32_e32 v82, 1.0, v82
	v_add_f32_e32 v83, 1.0, v83
	v_rcp_f32_e32 v82, v82
	v_rcp_f32_e32 v83, v83
	s_nop 0
	v_pk_mul_f32 v[80:81], v[80:81], v[82:83]
	s_nop 0
	v_pk_mul_f32 v[80:81], v[72:73], v[80:81]
	v_lshlrev_b32_e32 v72, 16, v143
	v_and_b32_e32 v73, 0xffff0000, v143
	v_pk_mul_f32 v[72:73], v[102:103], v[72:73]
	v_lshlrev_b32_e32 v82, 16, v169
	v_and_b32_e32 v83, 0xffff0000, v169
	v_pk_fma_f32 v[72:73], v[94:95], v[84:85], v[72:73]
	v_cndmask_b32_e64 v84, v138, v165, s[6:7]
	v_pk_fma_f32 v[72:73], v[90:91], v[82:83], v[72:73]
	s_nop 0
	v_pk_add_f32 v[72:73], v[98:99], v[72:73]
	s_nop 0
	v_mul_f32_e32 v82, 0xbfb8aa3b, v72
	v_mul_f32_e32 v83, 0xbfb8aa3b, v73
	v_exp_f32_e32 v82, v82
	v_exp_f32_e32 v83, v83
	v_add_f32_e32 v82, 1.0, v82
	v_add_f32_e32 v83, 1.0, v83
	v_rcp_f32_e32 v82, v82
	v_rcp_f32_e32 v83, v83
	s_nop 0
	v_pk_mul_f32 v[72:73], v[72:73], v[82:83]
	s_nop 0
	v_pk_mul_f32 v[82:83], v[74:75], v[72:73]
	v_cvt_pk_bf16_f32 v72, v76, v77
	v_mad_i64_i32 v[76:77], s[0:1], v106, s26, v[172:173]
	v_cvt_pk_bf16_f32 v73, v78, v79
	v_cvt_pk_bf16_f32 v74, v80, v81
	v_cvt_pk_bf16_f32 v75, v82, v83
	v_lshl_add_u64 v[132:133], v[76:77], 0, v[204:205]
	global_store_dwordx4 v[132:133], v[72:75], off
	ds_bpermute_b32 v72, v193, v128
	ds_bpermute_b32 v73, v193, v129
	v_mov_b32_dpp v74, v130 row_ror:1 row_mask:0xf bank_mask:0xf
	v_mov_b32_dpp v75, v131 row_ror:1 row_mask:0xf bank_mask:0xf
	v_cndmask_b32_e64 v77, v107, v168, s[6:7]
	s_waitcnt lgkmcnt(0)
	v_cndmask_b32_e64 v76, v72, v86, s[4:5]
	s_waitcnt lgkmcnt(0)
	v_cndmask_b32_e64 v79, v73, v87, s[4:5]
	v_lshlrev_b32_e32 v72, 16, v76
	v_and_b32_e32 v73, 0xffff0000, v76
	s_waitcnt lgkmcnt(0)
	v_cndmask_b32_e64 v81, v74, v104, s[4:5]
	s_waitcnt lgkmcnt(0)
	v_cndmask_b32_e64 v83, v75, v105, s[4:5]
	v_lshlrev_b32_e32 v74, 16, v77
	v_and_b32_e32 v75, 0xffff0000, v77
	v_pk_mul_f32 v[72:73], v[120:121], v[72:73]
	v_lshlrev_b32_e32 v76, 16, v128
	v_and_b32_e32 v77, 0xffff0000, v128
	v_pk_fma_f32 v[72:73], v[112:113], v[76:77], v[72:73]
	v_cndmask_b32_e64 v80, v136, v167, s[6:7]
	v_pk_fma_f32 v[72:73], v[108:109], v[74:75], v[72:73]
	v_lshlrev_b32_e32 v76, 16, v129
	v_pk_add_f32 v[72:73], v[116:117], v[72:73]
	v_and_b32_e32 v77, 0xffff0000, v129
	v_mul_f32_e32 v74, 0xbfb8aa3b, v72
	v_mul_f32_e32 v75, 0xbfb8aa3b, v73
	v_exp_f32_e32 v74, v74
	v_exp_f32_e32 v75, v75
	v_cndmask_b32_e64 v82, v137, v166, s[6:7]
	v_or_b32_e32 v78, 48, v164
	v_add_f32_e32 v74, 1.0, v74
	v_add_f32_e32 v75, 1.0, v75
	v_rcp_f32_e32 v74, v74
	v_rcp_f32_e32 v75, v75
	s_nop 0
	v_pk_mul_f32 v[72:73], v[72:73], v[74:75]
	s_nop 0
	v_pk_mul_f32 v[68:69], v[68:69], v[72:73]
	v_lshlrev_b32_e32 v72, 16, v79
	v_and_b32_e32 v73, 0xffff0000, v79
	v_pk_mul_f32 v[72:73], v[122:123], v[72:73]
	v_lshlrev_b32_e32 v74, 16, v80
	v_and_b32_e32 v75, 0xffff0000, v80
	v_pk_fma_f32 v[72:73], v[114:115], v[76:77], v[72:73]
	v_lshlrev_b32_e32 v76, 16, v130
	v_pk_fma_f32 v[72:73], v[110:111], v[74:75], v[72:73]
	v_and_b32_e32 v77, 0xffff0000, v130
	v_pk_add_f32 v[72:73], v[118:119], v[72:73]
	s_nop 0
	v_mul_f32_e32 v74, 0xbfb8aa3b, v72
	v_mul_f32_e32 v75, 0xbfb8aa3b, v73
	v_exp_f32_e32 v74, v74
	v_exp_f32_e32 v75, v75
	v_add_f32_e32 v74, 1.0, v74
	v_add_f32_e32 v75, 1.0, v75
	v_rcp_f32_e32 v74, v74
	v_rcp_f32_e32 v75, v75
	s_nop 0
	v_pk_mul_f32 v[72:73], v[72:73], v[74:75]
	s_nop 0
	v_pk_mul_f32 v[70:71], v[70:71], v[72:73]
	v_lshlrev_b32_e32 v72, 16, v81
	v_and_b32_e32 v73, 0xffff0000, v81
	v_pk_mul_f32 v[72:73], v[100:101], v[72:73]
	v_lshlrev_b32_e32 v74, 16, v82
	v_and_b32_e32 v75, 0xffff0000, v82
	v_pk_fma_f32 v[72:73], v[92:93], v[76:77], v[72:73]
	v_lshlrev_b32_e32 v76, 16, v131
	v_pk_fma_f32 v[72:73], v[88:89], v[74:75], v[72:73]
	v_and_b32_e32 v77, 0xffff0000, v131
	v_pk_add_f32 v[72:73], v[96:97], v[72:73]
	s_nop 0
	v_mul_f32_e32 v74, 0xbfb8aa3b, v72
	v_mul_f32_e32 v75, 0xbfb8aa3b, v73
	v_exp_f32_e32 v74, v74
	v_exp_f32_e32 v75, v75
	v_add_f32_e32 v74, 1.0, v74
	v_add_f32_e32 v75, 1.0, v75
	v_rcp_f32_e32 v74, v74
	v_rcp_f32_e32 v75, v75
	s_nop 0
	v_pk_mul_f32 v[72:73], v[72:73], v[74:75]
	s_nop 0
	v_pk_mul_f32 v[72:73], v[64:65], v[72:73]
	v_lshlrev_b32_e32 v64, 16, v83
	v_and_b32_e32 v65, 0xffff0000, v83
	v_pk_mul_f32 v[64:65], v[102:103], v[64:65]
	v_lshlrev_b32_e32 v74, 16, v84
	v_and_b32_e32 v75, 0xffff0000, v84
	v_pk_fma_f32 v[64:65], v[94:95], v[76:77], v[64:65]
	s_nop 0
	v_pk_fma_f32 v[64:65], v[90:91], v[74:75], v[64:65]
	s_nop 0
	v_pk_add_f32 v[64:65], v[98:99], v[64:65]
	s_nop 0
	v_mul_f32_e32 v74, 0xbfb8aa3b, v64
	v_mul_f32_e32 v75, 0xbfb8aa3b, v65
	v_exp_f32_e32 v74, v74
	v_exp_f32_e32 v75, v75
	v_add_f32_e32 v74, 1.0, v74
	v_add_f32_e32 v75, 1.0, v75
	v_rcp_f32_e32 v74, v74
	v_rcp_f32_e32 v75, v75
	s_nop 0
	v_pk_mul_f32 v[64:65], v[64:65], v[74:75]
	s_nop 0
	v_pk_mul_f32 v[74:75], v[66:67], v[64:65]
	v_cvt_pk_bf16_f32 v64, v68, v69
	v_mad_i64_i32 v[68:69], s[0:1], v78, s26, v[172:173]
	v_cvt_pk_bf16_f32 v65, v70, v71
	v_cvt_pk_bf16_f32 v66, v72, v73
	v_cvt_pk_bf16_f32 v67, v74, v75
	v_lshl_add_u64 v[112:113], v[68:69], 0, v[204:205]
	global_store_dwordx4 v[112:113], v[64:67], off
	s_mov_b64 s[0:1], -1
	s_nop 0
	v_or_b32_e32 v64, 0x80, v192
	v_ashrrev_i32_e32 v65, 31, v64
	v_lshlrev_b64 v[64:65], 2, v[64:65]
	v_lshl_add_u64 v[66:67], s[46:47], 0, v[64:65]
	v_lshl_add_u64 v[72:73], s[48:49], 0, v[64:65]
	global_load_dwordx4 v[76:79], v[190:191], off offset:528
	global_load_dwordx4 v[92:95], v[190:191], off offset:512
	global_load_dwordx4 v[68:71], v[66:67], off offset:16
	global_load_dwordx4 v[84:87], v[66:67], off
	s_nop 0
	global_load_dwordx4 v[64:67], v[72:73], off offset:16
	global_load_dwordx4 v[80:83], v[72:73], off
	s_nop 0
	global_load_dwordx4 v[72:75], v[188:189], off offset:528
	global_load_dwordx4 v[88:91], v[188:189], off offset:512
	global_load_dwordx4 v[108:111], v[194:195], off offset:256
	global_load_dwordx4 v[104:107], v[198:199], off offset:256
	global_load_dwordx4 v[100:103], v[200:201], off offset:256
	global_load_dwordx4 v[96:99], v[206:207], off offset:256
	global_load_dwordx4 v[114:117], v[196:197], off offset:256
	global_load_dwordx4 v[118:121], v[202:203], off offset:256
	s_waitcnt vmcnt(5)
	v_mov_b32_dpp v130, v108 row_ror:1 row_mask:0xf bank_mask:0xf
	s_waitcnt vmcnt(4)
	v_mov_b32_dpp v136, v104 row_ror:15 row_mask:0xf bank_mask:0xf
	v_mov_b32_dpp v137, v105 row_ror:15 row_mask:0xf bank_mask:0xf
	v_mov_b32_dpp v134, v110 row_ror:1 row_mask:0xf bank_mask:0xf
	s_waitcnt vmcnt(1)
	v_cndmask_b32_e64 v122, v117, 0, s[62:63]
	v_cndmask_b32_e64 v123, v116, 0, s[62:63]
	s_waitcnt vmcnt(0)
	v_cndmask_b32_e64 v116, v119, 0, s[50:51]
	v_cndmask_b32_e64 v117, v118, 0, s[50:51]
	v_mov_b32_dpp v118, v108 row_ror:15 row_mask:0xf bank_mask:0xf
	v_mov_b32_dpp v119, v109 row_ror:15 row_mask:0xf bank_mask:0xf
	v_mov_b32_dpp v135, v111 row_ror:1 row_mask:0xf bank_mask:0xf
	v_cndmask_b32_e64 v128, v115, 0, s[62:63]
	v_cndmask_b32_e64 v129, v114, 0, s[62:63]
	v_cndmask_b32_e64 v114, v121, 0, s[50:51]
	v_cndmask_b32_e64 v115, v120, 0, s[50:51]
	v_mov_b32_dpp v120, v110 row_ror:15 row_mask:0xf bank_mask:0xf
	v_mov_b32_dpp v121, v111 row_ror:15 row_mask:0xf bank_mask:0xf
	v_mov_b32_dpp v138, v106 row_ror:15 row_mask:0xf bank_mask:0xf
	v_mov_b32_dpp v139, v107 row_ror:15 row_mask:0xf bank_mask:0xf
	s_waitcnt lgkmcnt(0)
	v_cndmask_b32_e64 v129, v130, v129, s[4:5]
	s_waitcnt lgkmcnt(0)
	v_cndmask_b32_e64 v140, v118, v136, s[6:7]
	s_waitcnt lgkmcnt(0)
	v_cndmask_b32_e64 v141, v119, v137, s[6:7]
	v_lshlrev_b32_e32 v118, 16, v129
	v_and_b32_e32 v119, 0xffff0000, v129
	v_cndmask_b32_e64 v142, v134, v123, s[4:5]
	s_waitcnt lgkmcnt(0)
	v_cndmask_b32_e64 v164, v135, v122, s[4:5]
	v_pk_mul_f32 v[118:119], v[92:93], v[118:119]
	v_lshlrev_b32_e32 v122, 16, v108
	v_and_b32_e32 v123, 0xffff0000, v108
	s_waitcnt lgkmcnt(0)
	v_cndmask_b32_e64 v143, v120, v138, s[6:7]
	s_waitcnt lgkmcnt(0)
	v_cndmask_b32_e64 v165, v121, v139, s[6:7]
	v_lshlrev_b32_e32 v120, 16, v140
	v_and_b32_e32 v121, 0xffff0000, v140
	v_pk_fma_f32 v[118:119], v[84:85], v[122:123], v[118:119]
	v_mov_b32_dpp v131, v109 row_ror:1 row_mask:0xf bank_mask:0xf
	v_pk_fma_f32 v[118:119], v[80:81], v[120:121], v[118:119]
	s_waitcnt lgkmcnt(0)
	v_cndmask_b32_e64 v128, v131, v128, s[4:5]
	v_pk_add_f32 v[118:119], v[88:89], v[118:119]
	s_nop 0
	v_mul_f32_e32 v108, 0xbfb8aa3b, v118
	v_exp_f32_e32 v108, v108
	s_nop 0
	v_add_f32_e32 v108, 1.0, v108
	v_rcp_f32_e32 v120, v108
	v_mul_f32_e32 v108, 0xbfb8aa3b, v119
	v_exp_f32_e32 v108, v108
	s_nop 0
	v_add_f32_e32 v108, 1.0, v108
	v_rcp_f32_e32 v121, v108
	v_lshlrev_b32_e32 v108, 16, v109
	v_and_b32_e32 v109, 0xffff0000, v109
	v_pk_mul_f32 v[118:119], v[118:119], v[120:121]
	s_nop 0
	v_pk_mul_f32 v[60:61], v[60:61], v[118:119]
	v_lshlrev_b32_e32 v118, 16, v128
	v_and_b32_e32 v119, 0xffff0000, v128
	v_pk_mul_f32 v[118:119], v[94:95], v[118:119]
	v_lshlrev_b32_e32 v120, 16, v141
	v_and_b32_e32 v121, 0xffff0000, v141
	v_pk_fma_f32 v[108:109], v[86:87], v[108:109], v[118:119]
	s_nop 0
	v_pk_fma_f32 v[108:109], v[82:83], v[120:121], v[108:109]
	v_lshlrev_b32_e32 v120, 16, v110
	v_pk_add_f32 v[108:109], v[90:91], v[108:109]
	v_and_b32_e32 v121, 0xffff0000, v110
	v_mul_f32_e32 v118, 0xbfb8aa3b, v108
	v_mul_f32_e32 v119, 0xbfb8aa3b, v109
	v_exp_f32_e32 v118, v118
	v_exp_f32_e32 v119, v119
	v_add_f32_e32 v118, 1.0, v118
	v_add_f32_e32 v119, 1.0, v119
	v_rcp_f32_e32 v118, v118
	v_rcp_f32_e32 v119, v119
	s_nop 0
	v_pk_mul_f32 v[108:109], v[108:109], v[118:119]
	s_nop 0
	v_pk_mul_f32 v[62:63], v[62:63], v[108:109]
	v_lshlrev_b32_e32 v108, 16, v142
	v_and_b32_e32 v109, 0xffff0000, v142
	v_pk_mul_f32 v[108:109], v[76:77], v[108:109]
	v_lshlrev_b32_e32 v118, 16, v143
	v_and_b32_e32 v119, 0xffff0000, v143
	v_pk_fma_f32 v[108:109], v[68:69], v[120:121], v[108:109]
	s_nop 0
	v_pk_fma_f32 v[108:109], v[64:65], v[118:119], v[108:109]
	s_nop 0
	v_pk_add_f32 v[108:109], v[72:73], v[108:109]
	s_nop 0
	v_mul_f32_e32 v110, 0xbfb8aa3b, v108
	v_exp_f32_e32 v110, v110
	s_nop 0
	v_add_f32_e32 v110, 1.0, v110
	v_rcp_f32_e32 v118, v110
	v_mul_f32_e32 v110, 0xbfb8aa3b, v109
	v_exp_f32_e32 v110, v110
	s_nop 0
	v_add_f32_e32 v110, 1.0, v110
	v_rcp_f32_e32 v119, v110
	v_lshlrev_b32_e32 v110, 16, v111
	v_and_b32_e32 v111, 0xffff0000, v111
	v_pk_mul_f32 v[108:109], v[108:109], v[118:119]
	s_nop 0
	v_pk_mul_f32 v[108:109], v[56:57], v[108:109]
	v_lshlrev_b32_e32 v56, 16, v164
	v_and_b32_e32 v57, 0xffff0000, v164
	v_pk_mul_f32 v[56:57], v[78:79], v[56:57]
	v_lshlrev_b32_e32 v118, 16, v165
	v_and_b32_e32 v119, 0xffff0000, v165
	v_pk_fma_f32 v[56:57], v[70:71], v[110:111], v[56:57]
	s_nop 0
	v_pk_fma_f32 v[56:57], v[66:67], v[118:119], v[56:57]
	v_mov_b32_dpp v118, v102 row_ror:15 row_mask:0xf bank_mask:0xf
	v_pk_add_f32 v[56:57], v[74:75], v[56:57]
	v_mov_b32_dpp v119, v103 row_ror:15 row_mask:0xf bank_mask:0xf
	v_mul_f32_e32 v110, 0xbfb8aa3b, v56
	v_mul_f32_e32 v111, 0xbfb8aa3b, v57
	v_exp_f32_e32 v110, v110
	v_exp_f32_e32 v111, v111
	s_waitcnt lgkmcnt(0)
	v_cndmask_b32_e64 v123, v138, v118, s[6:7]
	s_waitcnt lgkmcnt(0)
	v_cndmask_b32_e64 v129, v139, v119, s[6:7]
	v_add_f32_e32 v110, 1.0, v110
	v_add_f32_e32 v111, 1.0, v111
	v_rcp_f32_e32 v110, v110
	v_rcp_f32_e32 v111, v111
	s_nop 0
	v_pk_mul_f32 v[56:57], v[56:57], v[110:111]
	s_nop 0
	v_pk_mul_f32 v[110:111], v[58:59], v[56:57]
	v_cvt_pk_bf16_f32 v57, v62, v63
	v_mov_b32_dpp v62, v104 row_ror:1 row_mask:0xf bank_mask:0xf
	v_cvt_pk_bf16_f32 v59, v110, v111
	v_mov_b32_dpp v110, v100 row_ror:15 row_mask:0xf bank_mask:0xf
	v_cvt_pk_bf16_f32 v56, v60, v61
	v_cvt_pk_bf16_f32 v58, v108, v109
	global_store_dwordx4 v[156:157], v[56:59], off offset:256
	v_lshlrev_b32_e32 v60, 16, v104
	v_and_b32_e32 v61, 0xffff0000, v104
	s_waitcnt lgkmcnt(0)
	v_cndmask_b32_e64 v57, v62, v130, s[4:5]
	v_lshlrev_b32_e32 v56, 16, v57
	v_and_b32_e32 v57, 0xffff0000, v57
	s_waitcnt lgkmcnt(0)
	v_cndmask_b32_e64 v59, v136, v110, s[6:7]
	v_pk_mul_f32 v[56:57], v[92:93], v[56:57]
	v_lshlrev_b32_e32 v58, 16, v59
	v_and_b32_e32 v59, 0xffff0000, v59
	v_pk_fma_f32 v[56:57], v[84:85], v[60:61], v[56:57]
	v_mov_b32_dpp v63, v105 row_ror:1 row_mask:0xf bank_mask:0xf
	v_pk_fma_f32 v[56:57], v[80:81], v[58:59], v[56:57]
	v_mov_b32_dpp v111, v101 row_ror:15 row_mask:0xf bank_mask:0xf
	v_pk_add_f32 v[56:57], v[88:89], v[56:57]
	v_lshlrev_b32_e32 v60, 16, v105
	v_mul_f32_e32 v58, 0xbfb8aa3b, v56
	v_mul_f32_e32 v59, 0xbfb8aa3b, v57
	v_exp_f32_e32 v58, v58
	v_exp_f32_e32 v59, v59
	s_waitcnt lgkmcnt(0)
	v_cndmask_b32_e64 v120, v63, v131, s[4:5]
	s_waitcnt lgkmcnt(0)
	v_cndmask_b32_e64 v121, v137, v111, s[6:7]
	v_add_f32_e32 v58, 1.0, v58
	v_add_f32_e32 v59, 1.0, v59
	v_rcp_f32_e32 v58, v58
	v_rcp_f32_e32 v59, v59
	v_and_b32_e32 v61, 0xffff0000, v105
	v_mov_b32_dpp v108, v106 row_ror:1 row_mask:0xf bank_mask:0xf
	v_mov_b32_dpp v109, v107 row_ror:1 row_mask:0xf bank_mask:0xf
	v_pk_mul_f32 v[56:57], v[56:57], v[58:59]
	v_lshlrev_b32_e32 v58, 16, v121
	v_pk_mul_f32 v[52:53], v[52:53], v[56:57]
	v_lshlrev_b32_e32 v56, 16, v120
	v_and_b32_e32 v57, 0xffff0000, v120
	v_pk_mul_f32 v[56:57], v[94:95], v[56:57]
	v_and_b32_e32 v59, 0xffff0000, v121
	v_pk_fma_f32 v[56:57], v[86:87], v[60:61], v[56:57]
	s_waitcnt lgkmcnt(0)
	v_cndmask_b32_e64 v122, v108, v134, s[4:5]
	v_pk_fma_f32 v[56:57], v[82:83], v[58:59], v[56:57]
	v_lshlrev_b32_e32 v60, 16, v106
	v_pk_add_f32 v[56:57], v[90:91], v[56:57]
	v_and_b32_e32 v61, 0xffff0000, v106
	v_mul_f32_e32 v58, 0xbfb8aa3b, v56
	v_mul_f32_e32 v59, 0xbfb8aa3b, v57
	v_exp_f32_e32 v58, v58
	v_exp_f32_e32 v59, v59
	s_waitcnt lgkmcnt(0)
	v_cndmask_b32_e64 v128, v109, v135, s[4:5]
	v_add_f32_e32 v58, 1.0, v58
	v_add_f32_e32 v59, 1.0, v59
	v_rcp_f32_e32 v58, v58
	v_rcp_f32_e32 v59, v59
	s_nop 0
	v_pk_mul_f32 v[56:57], v[56:57], v[58:59]
	s_nop 0
	v_pk_mul_f32 v[54:55], v[54:55], v[56:57]
	v_lshlrev_b32_e32 v56, 16, v122
	v_and_b32_e32 v57, 0xffff0000, v122
	v_pk_mul_f32 v[56:57], v[76:77], v[56:57]
	v_lshlrev_b32_e32 v58, 16, v123
	v_and_b32_e32 v59, 0xffff0000, v123
	v_pk_fma_f32 v[56:57], v[68:69], v[60:61], v[56:57]
	v_lshlrev_b32_e32 v60, 16, v107
	v_pk_fma_f32 v[56:57], v[64:65], v[58:59], v[56:57]
	v_and_b32_e32 v61, 0xffff0000, v107
	v_pk_add_f32 v[56:57], v[72:73], v[56:57]
	s_nop 0
	v_mul_f32_e32 v58, 0xbfb8aa3b, v56
	v_mul_f32_e32 v59, 0xbfb8aa3b, v57
	v_exp_f32_e32 v58, v58
	v_exp_f32_e32 v59, v59
	v_add_f32_e32 v58, 1.0, v58
	v_add_f32_e32 v59, 1.0, v59
	v_rcp_f32_e32 v58, v58
	v_rcp_f32_e32 v59, v59
	s_nop 0
	v_pk_mul_f32 v[56:57], v[56:57], v[58:59]
	s_nop 0
	v_pk_mul_f32 v[56:57], v[48:49], v[56:57]
	v_lshlrev_b32_e32 v48, 16, v128
	v_and_b32_e32 v49, 0xffff0000, v128
	v_pk_mul_f32 v[48:49], v[78:79], v[48:49]
	v_lshlrev_b32_e32 v58, 16, v129
	v_and_b32_e32 v59, 0xffff0000, v129
	v_pk_fma_f32 v[48:49], v[70:71], v[60:61], v[48:49]
	v_mov_b32_dpp v60, v98 row_ror:15 row_mask:0xf bank_mask:0xf
	v_pk_fma_f32 v[48:49], v[66:67], v[58:59], v[48:49]
	v_mov_b32_dpp v61, v99 row_ror:15 row_mask:0xf bank_mask:0xf
	v_pk_add_f32 v[48:49], v[74:75], v[48:49]
	s_waitcnt lgkmcnt(0)
	v_cndmask_b32_e64 v105, v118, v60, s[6:7]
	v_mul_f32_e32 v58, 0xbfb8aa3b, v48
	v_mul_f32_e32 v59, 0xbfb8aa3b, v49
	v_exp_f32_e32 v58, v58
	v_exp_f32_e32 v59, v59
	s_waitcnt lgkmcnt(0)
	v_cndmask_b32_e64 v107, v119, v61, s[6:7]
	v_add_f32_e32 v58, 1.0, v58
	v_add_f32_e32 v59, 1.0, v59
	v_rcp_f32_e32 v58, v58
	v_rcp_f32_e32 v59, v59
	s_nop 0
	v_pk_mul_f32 v[48:49], v[48:49], v[58:59]
	s_nop 0
	v_pk_mul_f32 v[58:59], v[50:51], v[48:49]
	v_cvt_pk_bf16_f32 v49, v54, v55
	v_mov_b32_dpp v54, v100 row_ror:1 row_mask:0xf bank_mask:0xf
	v_cvt_pk_bf16_f32 v51, v58, v59
	v_mov_b32_dpp v58, v96 row_ror:15 row_mask:0xf bank_mask:0xf
	v_cvt_pk_bf16_f32 v48, v52, v53
	v_cvt_pk_bf16_f32 v50, v56, v57
	global_store_dwordx4 v[146:147], v[48:51], off offset:256
	v_lshlrev_b32_e32 v52, 16, v100
	v_and_b32_e32 v53, 0xffff0000, v100
	s_waitcnt lgkmcnt(0)
	v_cndmask_b32_e64 v49, v54, v62, s[4:5]
	v_lshlrev_b32_e32 v48, 16, v49
	v_and_b32_e32 v49, 0xffff0000, v49
	s_waitcnt lgkmcnt(0)
	v_cndmask_b32_e64 v51, v110, v58, s[6:7]
	v_pk_mul_f32 v[48:49], v[92:93], v[48:49]
	v_lshlrev_b32_e32 v50, 16, v51
	v_and_b32_e32 v51, 0xffff0000, v51
	v_pk_fma_f32 v[48:49], v[84:85], v[52:53], v[48:49]
	v_mov_b32_dpp v55, v101 row_ror:1 row_mask:0xf bank_mask:0xf
	v_pk_fma_f32 v[48:49], v[80:81], v[50:51], v[48:49]
	v_mov_b32_dpp v59, v97 row_ror:15 row_mask:0xf bank_mask:0xf
	v_pk_add_f32 v[48:49], v[88:89], v[48:49]
	v_lshlrev_b32_e32 v52, 16, v101
	v_mul_f32_e32 v50, 0xbfb8aa3b, v48
	v_mul_f32_e32 v51, 0xbfb8aa3b, v49
	v_exp_f32_e32 v50, v50
	v_exp_f32_e32 v51, v51
	s_waitcnt lgkmcnt(0)
	v_cndmask_b32_e64 v62, v55, v63, s[4:5]
	s_waitcnt lgkmcnt(0)
	v_cndmask_b32_e64 v63, v111, v59, s[6:7]
	v_add_f32_e32 v50, 1.0, v50
	v_add_f32_e32 v51, 1.0, v51
	v_rcp_f32_e32 v50, v50
	v_rcp_f32_e32 v51, v51
	v_and_b32_e32 v53, 0xffff0000, v101
	v_mov_b32_dpp v56, v102 row_ror:1 row_mask:0xf bank_mask:0xf
	v_mov_b32_dpp v57, v103 row_ror:1 row_mask:0xf bank_mask:0xf
	v_pk_mul_f32 v[48:49], v[48:49], v[50:51]
	v_lshlrev_b32_e32 v50, 16, v63
	v_pk_mul_f32 v[44:45], v[44:45], v[48:49]
	v_lshlrev_b32_e32 v48, 16, v62
	v_and_b32_e32 v49, 0xffff0000, v62
	v_pk_mul_f32 v[48:49], v[94:95], v[48:49]
	v_and_b32_e32 v51, 0xffff0000, v63
	v_pk_fma_f32 v[48:49], v[86:87], v[52:53], v[48:49]
	s_waitcnt lgkmcnt(0)
	v_cndmask_b32_e64 v104, v56, v108, s[4:5]
	v_pk_fma_f32 v[48:49], v[82:83], v[50:51], v[48:49]
	v_lshlrev_b32_e32 v52, 16, v102
	v_pk_add_f32 v[48:49], v[90:91], v[48:49]
	v_and_b32_e32 v53, 0xffff0000, v102
	v_mul_f32_e32 v50, 0xbfb8aa3b, v48
	v_mul_f32_e32 v51, 0xbfb8aa3b, v49
	v_exp_f32_e32 v50, v50
	v_exp_f32_e32 v51, v51
	s_waitcnt lgkmcnt(0)
	v_cndmask_b32_e64 v106, v57, v109, s[4:5]
	v_add_f32_e32 v50, 1.0, v50
	v_add_f32_e32 v51, 1.0, v51
	v_rcp_f32_e32 v50, v50
	v_rcp_f32_e32 v51, v51
	s_nop 0
	v_pk_mul_f32 v[48:49], v[48:49], v[50:51]
	s_nop 0
	v_pk_mul_f32 v[46:47], v[46:47], v[48:49]
	v_lshlrev_b32_e32 v48, 16, v104
	v_and_b32_e32 v49, 0xffff0000, v104
	v_pk_mul_f32 v[48:49], v[76:77], v[48:49]
	v_lshlrev_b32_e32 v50, 16, v105
	v_and_b32_e32 v51, 0xffff0000, v105
	v_pk_fma_f32 v[48:49], v[68:69], v[52:53], v[48:49]
	v_lshlrev_b32_e32 v52, 16, v103
	v_pk_fma_f32 v[48:49], v[64:65], v[50:51], v[48:49]
	v_and_b32_e32 v53, 0xffff0000, v103
	v_pk_add_f32 v[48:49], v[72:73], v[48:49]
	s_nop 0
	v_mul_f32_e32 v50, 0xbfb8aa3b, v48
	v_mul_f32_e32 v51, 0xbfb8aa3b, v49
	v_exp_f32_e32 v50, v50
	v_exp_f32_e32 v51, v51
	v_add_f32_e32 v50, 1.0, v50
	v_add_f32_e32 v51, 1.0, v51
	v_rcp_f32_e32 v50, v50
	v_rcp_f32_e32 v51, v51
	s_nop 0
	v_pk_mul_f32 v[48:49], v[48:49], v[50:51]
	s_nop 0
	v_pk_mul_f32 v[48:49], v[40:41], v[48:49]
	v_lshlrev_b32_e32 v40, 16, v106
	v_and_b32_e32 v41, 0xffff0000, v106
	v_pk_mul_f32 v[40:41], v[78:79], v[40:41]
	v_lshlrev_b32_e32 v50, 16, v107
	v_and_b32_e32 v51, 0xffff0000, v107
	v_pk_fma_f32 v[40:41], v[70:71], v[52:53], v[40:41]
	s_nop 0
	v_pk_fma_f32 v[40:41], v[66:67], v[50:51], v[40:41]
	s_nop 0
	v_pk_add_f32 v[40:41], v[74:75], v[40:41]
	s_nop 0
	v_mul_f32_e32 v50, 0xbfb8aa3b, v40
	v_mul_f32_e32 v51, 0xbfb8aa3b, v41
	v_exp_f32_e32 v50, v50
	v_exp_f32_e32 v51, v51
	v_add_f32_e32 v50, 1.0, v50
	v_add_f32_e32 v51, 1.0, v51
	v_rcp_f32_e32 v50, v50
	v_rcp_f32_e32 v51, v51
	s_nop 0
	v_pk_mul_f32 v[40:41], v[40:41], v[50:51]
	s_nop 0
	v_pk_mul_f32 v[50:51], v[42:43], v[40:41]
	v_cvt_pk_bf16_f32 v40, v44, v45
	v_cvt_pk_bf16_f32 v41, v46, v47
	v_cvt_pk_bf16_f32 v42, v48, v49
	v_cvt_pk_bf16_f32 v43, v50, v51
	global_store_dwordx4 v[148:149], v[40:43], off offset:256
	ds_bpermute_b32 v40, v193, v96
	ds_bpermute_b32 v41, v193, v97
	v_mov_b32_dpp v42, v98 row_ror:1 row_mask:0xf bank_mask:0xf
	v_mov_b32_dpp v43, v99 row_ror:1 row_mask:0xf bank_mask:0xf
	v_cndmask_b32_e64 v45, v58, v117, s[6:7]
	s_waitcnt lgkmcnt(0)
	v_cndmask_b32_e64 v44, v40, v54, s[4:5]
	s_waitcnt lgkmcnt(0)
	v_cndmask_b32_e64 v46, v41, v55, s[4:5]
	v_lshlrev_b32_e32 v40, 16, v44
	v_and_b32_e32 v41, 0xffff0000, v44
	s_waitcnt lgkmcnt(0)
	v_cndmask_b32_e64 v48, v42, v56, s[4:5]
	s_waitcnt lgkmcnt(0)
	v_cndmask_b32_e64 v50, v43, v57, s[4:5]
	v_lshlrev_b32_e32 v42, 16, v45
	v_and_b32_e32 v43, 0xffff0000, v45
	v_pk_mul_f32 v[40:41], v[92:93], v[40:41]
	v_lshlrev_b32_e32 v44, 16, v96
	v_and_b32_e32 v45, 0xffff0000, v96
	v_pk_fma_f32 v[40:41], v[84:85], v[44:45], v[40:41]
	v_cndmask_b32_e64 v47, v59, v116, s[6:7]
	v_pk_fma_f32 v[40:41], v[80:81], v[42:43], v[40:41]
	v_lshlrev_b32_e32 v44, 16, v97
	v_pk_add_f32 v[40:41], v[88:89], v[40:41]
	v_and_b32_e32 v45, 0xffff0000, v97
	v_mul_f32_e32 v42, 0xbfb8aa3b, v40
	v_mul_f32_e32 v43, 0xbfb8aa3b, v41
	v_exp_f32_e32 v42, v42
	v_exp_f32_e32 v43, v43
	v_cndmask_b32_e64 v49, v60, v115, s[6:7]
	v_cndmask_b32_e64 v51, v61, v114, s[6:7]
	v_add_f32_e32 v42, 1.0, v42
	v_add_f32_e32 v43, 1.0, v43
	v_rcp_f32_e32 v42, v42
	v_rcp_f32_e32 v43, v43
	s_nop 0
	v_pk_mul_f32 v[40:41], v[40:41], v[42:43]
	s_nop 0
	v_pk_mul_f32 v[36:37], v[36:37], v[40:41]
	v_lshlrev_b32_e32 v40, 16, v46
	v_and_b32_e32 v41, 0xffff0000, v46
	v_pk_mul_f32 v[40:41], v[94:95], v[40:41]
	v_lshlrev_b32_e32 v42, 16, v47
	v_and_b32_e32 v43, 0xffff0000, v47
	v_pk_fma_f32 v[40:41], v[86:87], v[44:45], v[40:41]
	v_lshlrev_b32_e32 v44, 16, v98
	v_pk_fma_f32 v[40:41], v[82:83], v[42:43], v[40:41]
	v_and_b32_e32 v45, 0xffff0000, v98
	v_pk_add_f32 v[40:41], v[90:91], v[40:41]
	s_nop 0
	v_mul_f32_e32 v42, 0xbfb8aa3b, v40
	v_mul_f32_e32 v43, 0xbfb8aa3b, v41
	v_exp_f32_e32 v42, v42
	v_exp_f32_e32 v43, v43
	v_add_f32_e32 v42, 1.0, v42
	v_add_f32_e32 v43, 1.0, v43
	v_rcp_f32_e32 v42, v42
	v_rcp_f32_e32 v43, v43
	s_nop 0
	v_pk_mul_f32 v[40:41], v[40:41], v[42:43]
	s_nop 0
	v_pk_mul_f32 v[38:39], v[38:39], v[40:41]
	v_lshlrev_b32_e32 v40, 16, v48
	v_and_b32_e32 v41, 0xffff0000, v48
	v_pk_mul_f32 v[40:41], v[76:77], v[40:41]
	v_lshlrev_b32_e32 v42, 16, v49
	v_and_b32_e32 v43, 0xffff0000, v49
	v_pk_fma_f32 v[40:41], v[68:69], v[44:45], v[40:41]
	v_lshlrev_b32_e32 v44, 16, v99
	v_pk_fma_f32 v[40:41], v[64:65], v[42:43], v[40:41]
	v_and_b32_e32 v45, 0xffff0000, v99
	v_pk_add_f32 v[40:41], v[72:73], v[40:41]
	s_nop 0
	v_mul_f32_e32 v42, 0xbfb8aa3b, v40
	v_mul_f32_e32 v43, 0xbfb8aa3b, v41
	v_exp_f32_e32 v42, v42
	v_exp_f32_e32 v43, v43
	v_add_f32_e32 v42, 1.0, v42
	v_add_f32_e32 v43, 1.0, v43
	v_rcp_f32_e32 v42, v42
	v_rcp_f32_e32 v43, v43
	s_nop 0
	v_pk_mul_f32 v[40:41], v[40:41], v[42:43]
	s_nop 0
	v_pk_mul_f32 v[40:41], v[32:33], v[40:41]
	v_lshlrev_b32_e32 v32, 16, v50
	v_and_b32_e32 v33, 0xffff0000, v50
	v_pk_mul_f32 v[32:33], v[78:79], v[32:33]
	v_lshlrev_b32_e32 v42, 16, v51
	v_and_b32_e32 v43, 0xffff0000, v51
	v_pk_fma_f32 v[32:33], v[70:71], v[44:45], v[32:33]
	s_nop 0
	v_pk_fma_f32 v[32:33], v[66:67], v[42:43], v[32:33]
	s_nop 0
	v_pk_add_f32 v[32:33], v[74:75], v[32:33]
	s_nop 0
	v_mul_f32_e32 v42, 0xbfb8aa3b, v32
	v_mul_f32_e32 v43, 0xbfb8aa3b, v33
	v_exp_f32_e32 v42, v42
	v_exp_f32_e32 v43, v43
	v_add_f32_e32 v42, 1.0, v42
	v_add_f32_e32 v43, 1.0, v43
	v_rcp_f32_e32 v42, v42
	v_rcp_f32_e32 v43, v43
	s_nop 0
	v_pk_mul_f32 v[32:33], v[32:33], v[42:43]
	s_nop 0
	v_pk_mul_f32 v[42:43], v[34:35], v[32:33]
	v_cvt_pk_bf16_f32 v32, v36, v37
	v_cvt_pk_bf16_f32 v33, v38, v39
	v_cvt_pk_bf16_f32 v34, v40, v41
	v_cvt_pk_bf16_f32 v35, v42, v43
	global_store_dwordx4 v[144:145], v[32:35], off offset:256
	global_load_dwordx4 v[48:51], v[150:151], off offset:256
	global_load_dwordx4 v[44:47], v[152:153], off offset:256
	global_load_dwordx4 v[40:43], v[154:155], off offset:256
	global_load_dwordx4 v[32:35], v[158:159], off offset:256
	global_load_dwordx4 v[52:55], v[162:163], off offset:256
	global_load_dwordx4 v[36:39], v[160:161], off offset:256
	s_waitcnt vmcnt(5)
	v_mov_b32_dpp v58, v48 row_ror:1 row_mask:0xf bank_mask:0xf
	v_mov_b32_dpp v56, v48 row_ror:15 row_mask:0xf bank_mask:0xf
	v_mov_b32_dpp v59, v49 row_ror:1 row_mask:0xf bank_mask:0xf
	s_waitcnt vmcnt(4)
	v_mov_b32_dpp v96, v44 row_ror:15 row_mask:0xf bank_mask:0xf
	v_mov_b32_dpp v57, v49 row_ror:15 row_mask:0xf bank_mask:0xf
	v_mov_b32_dpp v60, v50 row_ror:1 row_mask:0xf bank_mask:0xf
	v_mov_b32_dpp v62, v51 row_ror:1 row_mask:0xf bank_mask:0xf
	v_mov_b32_dpp v97, v45 row_ror:15 row_mask:0xf bank_mask:0xf
	s_waitcnt vmcnt(1)
	v_cndmask_b32_e64 v52, v52, 0, s[22:23]
	v_cndmask_b32_e64 v53, v53, 0, s[22:23]
	s_waitcnt lgkmcnt(0)
	v_cndmask_b32_e64 v100, v58, v52, s[4:5]
	v_cndmask_b32_e64 v55, v55, 0, s[22:23]
	v_cndmask_b32_e64 v54, v54, 0, s[22:23]
	s_waitcnt lgkmcnt(0)
	v_cndmask_b32_e64 v56, v56, v96, s[6:7]
	v_cndmask_b32_e64 v101, v59, v53, s[4:5]
	v_lshlrev_b32_e32 v52, 16, v100
	v_and_b32_e32 v53, 0xffff0000, v100
	s_waitcnt lgkmcnt(0)
	v_cndmask_b32_e64 v102, v57, v97, s[6:7]
	v_cndmask_b32_e64 v103, v60, v54, s[4:5]
	v_cndmask_b32_e64 v104, v62, v55, s[4:5]
	v_lshlrev_b32_e32 v54, 16, v56
	v_and_b32_e32 v55, 0xffff0000, v56
	v_pk_mul_f32 v[52:53], v[92:93], v[52:53]
	v_lshlrev_b32_e32 v56, 16, v48
	v_and_b32_e32 v57, 0xffff0000, v48
	v_pk_fma_f32 v[52:53], v[84:85], v[56:57], v[52:53]
	v_mov_b32_dpp v61, v50 row_ror:15 row_mask:0xf bank_mask:0xf
	v_pk_fma_f32 v[52:53], v[80:81], v[54:55], v[52:53]
	v_mov_b32_dpp v98, v46 row_ror:15 row_mask:0xf bank_mask:0xf
	v_pk_add_f32 v[52:53], v[88:89], v[52:53]
	v_mov_b32_dpp v63, v51 row_ror:15 row_mask:0xf bank_mask:0xf
	v_mul_f32_e32 v48, 0xbfb8aa3b, v52
	v_exp_f32_e32 v48, v48
	s_waitcnt lgkmcnt(0)
	v_cndmask_b32_e64 v61, v61, v98, s[6:7]
	v_mov_b32_dpp v99, v47 row_ror:15 row_mask:0xf bank_mask:0xf
	v_add_f32_e32 v48, 1.0, v48
	v_rcp_f32_e32 v54, v48
	v_mul_f32_e32 v48, 0xbfb8aa3b, v53
	v_exp_f32_e32 v48, v48
	s_waitcnt lgkmcnt(0)
	v_cndmask_b32_e64 v63, v63, v99, s[6:7]
	v_add_f32_e32 v48, 1.0, v48
	v_rcp_f32_e32 v55, v48
	v_lshlrev_b32_e32 v48, 16, v49
	v_and_b32_e32 v49, 0xffff0000, v49
	v_pk_mul_f32 v[52:53], v[52:53], v[54:55]
	s_nop 0
	v_pk_mul_f32 v[28:29], v[28:29], v[52:53]
	v_lshlrev_b32_e32 v52, 16, v101
	v_and_b32_e32 v53, 0xffff0000, v101
	v_pk_mul_f32 v[52:53], v[94:95], v[52:53]
	v_lshlrev_b32_e32 v54, 16, v102
	v_and_b32_e32 v55, 0xffff0000, v102
	v_pk_fma_f32 v[48:49], v[86:87], v[48:49], v[52:53]
	s_nop 0
	v_pk_fma_f32 v[48:49], v[82:83], v[54:55], v[48:49]
	v_lshlrev_b32_e32 v54, 16, v50
	v_pk_add_f32 v[48:49], v[90:91], v[48:49]
	v_and_b32_e32 v55, 0xffff0000, v50
	v_mul_f32_e32 v52, 0xbfb8aa3b, v48
	v_mul_f32_e32 v53, 0xbfb8aa3b, v49
	v_exp_f32_e32 v52, v52
	v_exp_f32_e32 v53, v53
	v_add_f32_e32 v52, 1.0, v52
	v_add_f32_e32 v53, 1.0, v53
	v_rcp_f32_e32 v52, v52
	v_rcp_f32_e32 v53, v53
	s_nop 0
	v_pk_mul_f32 v[48:49], v[48:49], v[52:53]
	s_nop 0
	v_pk_mul_f32 v[30:31], v[30:31], v[48:49]
	v_lshlrev_b32_e32 v48, 16, v103
	v_and_b32_e32 v49, 0xffff0000, v103
	v_pk_mul_f32 v[48:49], v[76:77], v[48:49]
	v_lshlrev_b32_e32 v52, 16, v61
	v_and_b32_e32 v53, 0xffff0000, v61
	v_pk_fma_f32 v[48:49], v[68:69], v[54:55], v[48:49]
	s_nop 0
	v_pk_fma_f32 v[48:49], v[64:65], v[52:53], v[48:49]
	s_nop 0
	v_pk_add_f32 v[48:49], v[72:73], v[48:49]
	s_nop 0
	v_mul_f32_e32 v50, 0xbfb8aa3b, v48
	v_exp_f32_e32 v50, v50
	s_nop 0
	v_add_f32_e32 v50, 1.0, v50
	v_rcp_f32_e32 v52, v50
	v_mul_f32_e32 v50, 0xbfb8aa3b, v49
	v_exp_f32_e32 v50, v50
	s_nop 0
	v_add_f32_e32 v50, 1.0, v50
	v_rcp_f32_e32 v53, v50
	v_lshlrev_b32_e32 v50, 16, v51
	v_and_b32_e32 v51, 0xffff0000, v51
	v_pk_mul_f32 v[48:49], v[48:49], v[52:53]
	s_nop 0
	v_pk_mul_f32 v[48:49], v[24:25], v[48:49]
	v_lshlrev_b32_e32 v24, 16, v104
	v_and_b32_e32 v25, 0xffff0000, v104
	v_pk_mul_f32 v[24:25], v[78:79], v[24:25]
	v_lshlrev_b32_e32 v52, 16, v63
	v_and_b32_e32 v53, 0xffff0000, v63
	v_pk_fma_f32 v[24:25], v[70:71], v[50:51], v[24:25]
	s_nop 0
	v_pk_fma_f32 v[24:25], v[66:67], v[52:53], v[24:25]
	v_mov_b32_dpp v52, v42 row_ror:15 row_mask:0xf bank_mask:0xf
	v_pk_add_f32 v[24:25], v[74:75], v[24:25]
	v_mov_b32_dpp v53, v43 row_ror:15 row_mask:0xf bank_mask:0xf
	v_mul_f32_e32 v50, 0xbfb8aa3b, v24
	v_mul_f32_e32 v51, 0xbfb8aa3b, v25
	v_exp_f32_e32 v50, v50
	v_exp_f32_e32 v51, v51
	s_waitcnt lgkmcnt(0)
	v_cndmask_b32_e64 v57, v98, v52, s[6:7]
	v_add_f32_e32 v50, 1.0, v50
	v_add_f32_e32 v51, 1.0, v51
	v_rcp_f32_e32 v50, v50
	v_rcp_f32_e32 v51, v51
	s_nop 0
	v_pk_mul_f32 v[24:25], v[24:25], v[50:51]
	s_nop 0
	v_pk_mul_f32 v[50:51], v[26:27], v[24:25]
	v_cvt_pk_bf16_f32 v25, v30, v31
	v_mov_b32_dpp v30, v44 row_ror:1 row_mask:0xf bank_mask:0xf
	v_cvt_pk_bf16_f32 v27, v50, v51
	v_mov_b32_dpp v50, v40 row_ror:15 row_mask:0xf bank_mask:0xf
	v_cvt_pk_bf16_f32 v24, v28, v29
	v_cvt_pk_bf16_f32 v26, v48, v49
	global_store_dwordx4 v[124:125], v[24:27], off offset:256
	v_lshlrev_b32_e32 v28, 16, v44
	v_and_b32_e32 v29, 0xffff0000, v44
	s_waitcnt lgkmcnt(0)
	v_cndmask_b32_e64 v25, v30, v58, s[4:5]
	v_lshlrev_b32_e32 v24, 16, v25
	v_and_b32_e32 v25, 0xffff0000, v25
	s_waitcnt lgkmcnt(0)
	v_cndmask_b32_e64 v27, v96, v50, s[6:7]
	v_pk_mul_f32 v[24:25], v[92:93], v[24:25]
	v_lshlrev_b32_e32 v26, 16, v27
	v_and_b32_e32 v27, 0xffff0000, v27
	v_pk_fma_f32 v[24:25], v[84:85], v[28:29], v[24:25]
	v_mov_b32_dpp v31, v45 row_ror:1 row_mask:0xf bank_mask:0xf
	v_pk_fma_f32 v[24:25], v[80:81], v[26:27], v[24:25]
	v_mov_b32_dpp v51, v41 row_ror:15 row_mask:0xf bank_mask:0xf
	v_pk_add_f32 v[24:25], v[88:89], v[24:25]
	v_lshlrev_b32_e32 v28, 16, v45
	v_mul_f32_e32 v26, 0xbfb8aa3b, v24
	v_mul_f32_e32 v27, 0xbfb8aa3b, v25
	v_exp_f32_e32 v26, v26
	v_exp_f32_e32 v27, v27
	s_waitcnt lgkmcnt(0)
	v_cndmask_b32_e64 v54, v31, v59, s[4:5]
	s_waitcnt lgkmcnt(0)
	v_cndmask_b32_e64 v55, v97, v51, s[6:7]
	v_add_f32_e32 v26, 1.0, v26
	v_add_f32_e32 v27, 1.0, v27
	v_rcp_f32_e32 v26, v26
	v_rcp_f32_e32 v27, v27
	v_and_b32_e32 v29, 0xffff0000, v45
	v_mov_b32_dpp v48, v46 row_ror:1 row_mask:0xf bank_mask:0xf
	v_mov_b32_dpp v49, v47 row_ror:1 row_mask:0xf bank_mask:0xf
	v_pk_mul_f32 v[24:25], v[24:25], v[26:27]
	v_lshlrev_b32_e32 v26, 16, v55
	v_pk_mul_f32 v[20:21], v[20:21], v[24:25]
	v_lshlrev_b32_e32 v24, 16, v54
	v_and_b32_e32 v25, 0xffff0000, v54
	v_pk_mul_f32 v[24:25], v[94:95], v[24:25]
	v_and_b32_e32 v27, 0xffff0000, v55
	v_pk_fma_f32 v[24:25], v[86:87], v[28:29], v[24:25]
	s_waitcnt lgkmcnt(0)
	v_cndmask_b32_e64 v56, v48, v60, s[4:5]
	v_pk_fma_f32 v[24:25], v[82:83], v[26:27], v[24:25]
	v_lshlrev_b32_e32 v28, 16, v46
	v_pk_add_f32 v[24:25], v[90:91], v[24:25]
	v_and_b32_e32 v29, 0xffff0000, v46
	v_mul_f32_e32 v26, 0xbfb8aa3b, v24
	v_mul_f32_e32 v27, 0xbfb8aa3b, v25
	v_exp_f32_e32 v26, v26
	v_exp_f32_e32 v27, v27
	s_waitcnt lgkmcnt(0)
	v_cndmask_b32_e64 v58, v49, v62, s[4:5]
	v_cndmask_b32_e64 v59, v99, v53, s[6:7]
	v_add_f32_e32 v26, 1.0, v26
	v_add_f32_e32 v27, 1.0, v27
	v_rcp_f32_e32 v26, v26
	v_rcp_f32_e32 v27, v27
	s_nop 0
	v_pk_mul_f32 v[24:25], v[24:25], v[26:27]
	s_nop 0
	v_pk_mul_f32 v[22:23], v[22:23], v[24:25]
	v_lshlrev_b32_e32 v24, 16, v56
	v_and_b32_e32 v25, 0xffff0000, v56
	v_pk_mul_f32 v[24:25], v[76:77], v[24:25]
	v_lshlrev_b32_e32 v26, 16, v57
	v_and_b32_e32 v27, 0xffff0000, v57
	v_pk_fma_f32 v[24:25], v[68:69], v[28:29], v[24:25]
	v_lshlrev_b32_e32 v28, 16, v47
	v_pk_fma_f32 v[24:25], v[64:65], v[26:27], v[24:25]
	v_and_b32_e32 v29, 0xffff0000, v47
	v_pk_add_f32 v[24:25], v[72:73], v[24:25]
	s_nop 0
	v_mul_f32_e32 v26, 0xbfb8aa3b, v24
	v_mul_f32_e32 v27, 0xbfb8aa3b, v25
	v_exp_f32_e32 v26, v26
	v_exp_f32_e32 v27, v27
	v_add_f32_e32 v26, 1.0, v26
	v_add_f32_e32 v27, 1.0, v27
	v_rcp_f32_e32 v26, v26
	v_rcp_f32_e32 v27, v27
	s_nop 0
	v_pk_mul_f32 v[24:25], v[24:25], v[26:27]
	s_nop 0
	v_pk_mul_f32 v[24:25], v[16:17], v[24:25]
	v_lshlrev_b32_e32 v16, 16, v58
	v_and_b32_e32 v17, 0xffff0000, v58
	v_pk_mul_f32 v[16:17], v[78:79], v[16:17]
	v_lshlrev_b32_e32 v26, 16, v59
	v_and_b32_e32 v27, 0xffff0000, v59
	v_pk_fma_f32 v[16:17], v[70:71], v[28:29], v[16:17]
	v_mov_b32_dpp v28, v34 row_ror:15 row_mask:0xf bank_mask:0xf
	v_pk_fma_f32 v[16:17], v[66:67], v[26:27], v[16:17]
	v_mov_b32_dpp v29, v35 row_ror:15 row_mask:0xf bank_mask:0xf
	v_pk_add_f32 v[16:17], v[74:75], v[16:17]
	s_waitcnt lgkmcnt(0)
	v_cndmask_b32_e64 v45, v52, v28, s[6:7]
	v_mul_f32_e32 v26, 0xbfb8aa3b, v16
	v_mul_f32_e32 v27, 0xbfb8aa3b, v17
	v_exp_f32_e32 v26, v26
	v_exp_f32_e32 v27, v27
	s_waitcnt lgkmcnt(0)
	v_cndmask_b32_e64 v47, v53, v29, s[6:7]
	v_add_f32_e32 v26, 1.0, v26
	v_add_f32_e32 v27, 1.0, v27
	v_rcp_f32_e32 v26, v26
	v_rcp_f32_e32 v27, v27
	s_nop 0
	v_pk_mul_f32 v[16:17], v[16:17], v[26:27]
	s_nop 0
	v_pk_mul_f32 v[26:27], v[18:19], v[16:17]
	v_cvt_pk_bf16_f32 v17, v22, v23
	v_mov_b32_dpp v22, v40 row_ror:1 row_mask:0xf bank_mask:0xf
	v_cvt_pk_bf16_f32 v19, v26, v27
	v_mov_b32_dpp v26, v32 row_ror:15 row_mask:0xf bank_mask:0xf
	v_cvt_pk_bf16_f32 v16, v20, v21
	v_cvt_pk_bf16_f32 v18, v24, v25
	global_store_dwordx4 v[126:127], v[16:19], off offset:256
	v_lshlrev_b32_e32 v20, 16, v40
	v_and_b32_e32 v21, 0xffff0000, v40
	s_waitcnt lgkmcnt(0)
	v_cndmask_b32_e64 v17, v22, v30, s[4:5]
	v_lshlrev_b32_e32 v16, 16, v17
	v_and_b32_e32 v17, 0xffff0000, v17
	s_waitcnt lgkmcnt(0)
	v_cndmask_b32_e64 v19, v50, v26, s[6:7]
	v_pk_mul_f32 v[16:17], v[92:93], v[16:17]
	v_lshlrev_b32_e32 v18, 16, v19
	v_and_b32_e32 v19, 0xffff0000, v19
	v_pk_fma_f32 v[16:17], v[84:85], v[20:21], v[16:17]
	v_mov_b32_dpp v23, v41 row_ror:1 row_mask:0xf bank_mask:0xf
	v_pk_fma_f32 v[16:17], v[80:81], v[18:19], v[16:17]
	v_mov_b32_dpp v27, v33 row_ror:15 row_mask:0xf bank_mask:0xf
	v_pk_add_f32 v[16:17], v[88:89], v[16:17]
	v_lshlrev_b32_e32 v20, 16, v41
	v_mul_f32_e32 v18, 0xbfb8aa3b, v16
	v_mul_f32_e32 v19, 0xbfb8aa3b, v17
	v_exp_f32_e32 v18, v18
	v_exp_f32_e32 v19, v19
	s_waitcnt lgkmcnt(0)
	v_cndmask_b32_e64 v30, v23, v31, s[4:5]
	s_waitcnt lgkmcnt(0)
	v_cndmask_b32_e64 v31, v51, v27, s[6:7]
	v_add_f32_e32 v18, 1.0, v18
	v_add_f32_e32 v19, 1.0, v19
	v_rcp_f32_e32 v18, v18
	v_rcp_f32_e32 v19, v19
	v_and_b32_e32 v21, 0xffff0000, v41
	v_mov_b32_dpp v24, v42 row_ror:1 row_mask:0xf bank_mask:0xf
	v_mov_b32_dpp v25, v43 row_ror:1 row_mask:0xf bank_mask:0xf
	v_pk_mul_f32 v[16:17], v[16:17], v[18:19]
	v_lshlrev_b32_e32 v18, 16, v31
	v_pk_mul_f32 v[12:13], v[12:13], v[16:17]
	v_lshlrev_b32_e32 v16, 16, v30
	v_and_b32_e32 v17, 0xffff0000, v30
	v_pk_mul_f32 v[16:17], v[94:95], v[16:17]
	v_and_b32_e32 v19, 0xffff0000, v31
	v_pk_fma_f32 v[16:17], v[86:87], v[20:21], v[16:17]
	s_waitcnt lgkmcnt(0)
	v_cndmask_b32_e64 v44, v24, v48, s[4:5]
	v_pk_fma_f32 v[16:17], v[82:83], v[18:19], v[16:17]
	v_lshlrev_b32_e32 v20, 16, v42
	v_pk_add_f32 v[16:17], v[90:91], v[16:17]
	v_and_b32_e32 v21, 0xffff0000, v42
	v_mul_f32_e32 v18, 0xbfb8aa3b, v16
	v_mul_f32_e32 v19, 0xbfb8aa3b, v17
	v_exp_f32_e32 v18, v18
	v_exp_f32_e32 v19, v19
	s_waitcnt lgkmcnt(0)
	v_cndmask_b32_e64 v46, v25, v49, s[4:5]
	v_add_f32_e32 v18, 1.0, v18
	v_add_f32_e32 v19, 1.0, v19
	v_rcp_f32_e32 v18, v18
	v_rcp_f32_e32 v19, v19
	s_nop 0
	v_pk_mul_f32 v[16:17], v[16:17], v[18:19]
	s_nop 0
	v_pk_mul_f32 v[14:15], v[14:15], v[16:17]
	v_lshlrev_b32_e32 v16, 16, v44
	v_and_b32_e32 v17, 0xffff0000, v44
	v_pk_mul_f32 v[16:17], v[76:77], v[16:17]
	v_lshlrev_b32_e32 v18, 16, v45
	v_and_b32_e32 v19, 0xffff0000, v45
	v_pk_fma_f32 v[16:17], v[68:69], v[20:21], v[16:17]
	v_lshlrev_b32_e32 v20, 16, v43
	v_pk_fma_f32 v[16:17], v[64:65], v[18:19], v[16:17]
	v_and_b32_e32 v21, 0xffff0000, v43
	v_pk_add_f32 v[16:17], v[72:73], v[16:17]
	s_nop 0
	v_mul_f32_e32 v18, 0xbfb8aa3b, v16
	v_mul_f32_e32 v19, 0xbfb8aa3b, v17
	v_exp_f32_e32 v18, v18
	v_exp_f32_e32 v19, v19
	v_add_f32_e32 v18, 1.0, v18
	v_add_f32_e32 v19, 1.0, v19
	v_rcp_f32_e32 v18, v18
	v_rcp_f32_e32 v19, v19
	s_nop 0
	v_pk_mul_f32 v[16:17], v[16:17], v[18:19]
	s_nop 0
	v_pk_mul_f32 v[16:17], v[8:9], v[16:17]
	v_lshlrev_b32_e32 v8, 16, v46
	v_and_b32_e32 v9, 0xffff0000, v46
	v_pk_mul_f32 v[8:9], v[78:79], v[8:9]
	v_lshlrev_b32_e32 v18, 16, v47
	v_and_b32_e32 v19, 0xffff0000, v47
	v_pk_fma_f32 v[8:9], v[70:71], v[20:21], v[8:9]
	s_nop 0
	v_pk_fma_f32 v[8:9], v[66:67], v[18:19], v[8:9]
	s_nop 0
	v_pk_add_f32 v[8:9], v[74:75], v[8:9]
	s_nop 0
	v_mul_f32_e32 v18, 0xbfb8aa3b, v8
	v_mul_f32_e32 v19, 0xbfb8aa3b, v9
	v_exp_f32_e32 v18, v18
	v_exp_f32_e32 v19, v19
	v_add_f32_e32 v18, 1.0, v18
	v_add_f32_e32 v19, 1.0, v19
	v_rcp_f32_e32 v18, v18
	v_rcp_f32_e32 v19, v19
	s_nop 0
	v_pk_mul_f32 v[8:9], v[8:9], v[18:19]
	s_nop 0
	v_pk_mul_f32 v[18:19], v[10:11], v[8:9]
	v_cvt_pk_bf16_f32 v8, v12, v13
	v_cvt_pk_bf16_f32 v9, v14, v15
	v_cvt_pk_bf16_f32 v10, v16, v17
	v_cvt_pk_bf16_f32 v11, v18, v19
	global_store_dwordx4 v[132:133], v[8:11], off offset:256
	ds_bpermute_b32 v8, v193, v32
	ds_bpermute_b32 v9, v193, v33
	v_mov_b32_dpp v10, v34 row_ror:1 row_mask:0xf bank_mask:0xf
	v_mov_b32_dpp v11, v35 row_ror:1 row_mask:0xf bank_mask:0xf
	s_waitcnt vmcnt(3)
	v_cndmask_b32_e64 v12, v39, 0, vcc
	s_waitcnt lgkmcnt(0)
	v_cndmask_b32_e64 v16, v8, v22, s[4:5]
	v_cndmask_b32_e64 v13, v38, 0, vcc
	v_cndmask_b32_e64 v15, v36, 0, vcc
	s_waitcnt lgkmcnt(0)
	v_cndmask_b32_e64 v17, v9, v23, s[4:5]
	v_lshlrev_b32_e32 v8, 16, v16
	v_and_b32_e32 v9, 0xffff0000, v16
	v_cndmask_b32_e64 v15, v26, v15, s[6:7]
	v_cndmask_b32_e64 v19, v28, v13, s[6:7]
	v_cndmask_b32_e64 v21, v29, v12, s[6:7]
	v_pk_mul_f32 v[8:9], v[92:93], v[8:9]
	v_lshlrev_b32_e32 v12, 16, v32
	v_and_b32_e32 v13, 0xffff0000, v32
	s_waitcnt lgkmcnt(0)
	v_cndmask_b32_e64 v18, v10, v24, s[4:5]
	s_waitcnt lgkmcnt(0)
	v_cndmask_b32_e64 v20, v11, v25, s[4:5]
	v_lshlrev_b32_e32 v10, 16, v15
	v_and_b32_e32 v11, 0xffff0000, v15
	v_pk_fma_f32 v[8:9], v[84:85], v[12:13], v[8:9]
	v_cndmask_b32_e64 v14, v37, 0, vcc
	v_pk_fma_f32 v[8:9], v[80:81], v[10:11], v[8:9]
	v_cndmask_b32_e64 v14, v27, v14, s[6:7]
	v_pk_add_f32 v[8:9], v[88:89], v[8:9]
	v_lshlrev_b32_e32 v12, 16, v33
	v_mul_f32_e32 v10, 0xbfb8aa3b, v8
	v_mul_f32_e32 v11, 0xbfb8aa3b, v9
	v_exp_f32_e32 v10, v10
	v_exp_f32_e32 v11, v11
	v_and_b32_e32 v13, 0xffff0000, v33
	s_andn2_b64 vcc, exec, s[68:69]
	v_add_f32_e32 v10, 1.0, v10
	v_add_f32_e32 v11, 1.0, v11
	v_rcp_f32_e32 v10, v10
	v_rcp_f32_e32 v11, v11
	s_nop 0
	v_pk_mul_f32 v[8:9], v[8:9], v[10:11]
	s_nop 0
	v_pk_mul_f32 v[4:5], v[4:5], v[8:9]
	v_lshlrev_b32_e32 v8, 16, v17
	v_and_b32_e32 v9, 0xffff0000, v17
	v_pk_mul_f32 v[8:9], v[94:95], v[8:9]
	v_lshlrev_b32_e32 v10, 16, v14
	v_and_b32_e32 v11, 0xffff0000, v14
	v_pk_fma_f32 v[8:9], v[86:87], v[12:13], v[8:9]
	v_lshlrev_b32_e32 v12, 16, v34
	v_pk_fma_f32 v[8:9], v[82:83], v[10:11], v[8:9]
	v_and_b32_e32 v13, 0xffff0000, v34
	v_pk_add_f32 v[8:9], v[90:91], v[8:9]
	s_nop 0
	v_mul_f32_e32 v10, 0xbfb8aa3b, v8
	v_mul_f32_e32 v11, 0xbfb8aa3b, v9
	v_exp_f32_e32 v10, v10
	v_exp_f32_e32 v11, v11
	v_add_f32_e32 v10, 1.0, v10
	v_add_f32_e32 v11, 1.0, v11
	v_rcp_f32_e32 v10, v10
	v_rcp_f32_e32 v11, v11
	s_nop 0
	v_pk_mul_f32 v[8:9], v[8:9], v[10:11]
	s_nop 0
	v_pk_mul_f32 v[6:7], v[6:7], v[8:9]
	v_lshlrev_b32_e32 v8, 16, v18
	v_and_b32_e32 v9, 0xffff0000, v18
	v_pk_mul_f32 v[8:9], v[76:77], v[8:9]
	v_lshlrev_b32_e32 v10, 16, v19
	v_and_b32_e32 v11, 0xffff0000, v19
	v_pk_fma_f32 v[8:9], v[68:69], v[12:13], v[8:9]
	v_lshlrev_b32_e32 v12, 16, v35
	v_pk_fma_f32 v[8:9], v[64:65], v[10:11], v[8:9]
	v_and_b32_e32 v13, 0xffff0000, v35
	v_pk_add_f32 v[8:9], v[72:73], v[8:9]
	s_nop 0
	v_mul_f32_e32 v10, 0xbfb8aa3b, v8
	v_mul_f32_e32 v11, 0xbfb8aa3b, v9
	v_exp_f32_e32 v10, v10
	v_exp_f32_e32 v11, v11
	v_add_f32_e32 v10, 1.0, v10
	v_add_f32_e32 v11, 1.0, v11
	v_rcp_f32_e32 v10, v10
	v_rcp_f32_e32 v11, v11
	s_nop 0
	v_pk_mul_f32 v[8:9], v[8:9], v[10:11]
	s_nop 0
	v_pk_mul_f32 v[8:9], v[0:1], v[8:9]
	v_lshlrev_b32_e32 v0, 16, v20
	v_and_b32_e32 v1, 0xffff0000, v20
	v_pk_mul_f32 v[0:1], v[78:79], v[0:1]
	v_lshlrev_b32_e32 v10, 16, v21
	v_and_b32_e32 v11, 0xffff0000, v21
	v_pk_fma_f32 v[0:1], v[70:71], v[12:13], v[0:1]
	s_nop 0
	v_pk_fma_f32 v[0:1], v[66:67], v[10:11], v[0:1]
	s_nop 0
	v_pk_add_f32 v[0:1], v[74:75], v[0:1]
	s_nop 0
	v_mul_f32_e32 v10, 0xbfb8aa3b, v0
	v_mul_f32_e32 v11, 0xbfb8aa3b, v1
	v_exp_f32_e32 v10, v10
	v_exp_f32_e32 v11, v11
	v_add_f32_e32 v10, 1.0, v10
	v_add_f32_e32 v11, 1.0, v11
	v_rcp_f32_e32 v10, v10
	v_rcp_f32_e32 v11, v11
	s_nop 0
	v_pk_mul_f32 v[0:1], v[0:1], v[10:11]
	s_nop 0
	v_pk_mul_f32 v[10:11], v[2:3], v[0:1]
	v_cvt_pk_bf16_f32 v0, v4, v5
	v_cvt_pk_bf16_f32 v1, v6, v7
	v_cvt_pk_bf16_f32 v2, v8, v9
	v_cvt_pk_bf16_f32 v3, v10, v11
	global_store_dwordx4 v[112:113], v[0:3], off offset:256
	s_cbranch_vccnz .LBB0_1053
	s_andn2_b64 vcc, exec, s[36:37]
	s_cbranch_vccnz .LBB0_1052
	s_barrier
	s_branch .LBB0_1052
